# v37 minus the 16 back-to-back s_setprio 0/1 toggle pairs between the two MFMA groups of each GEMM super-phase
# baseline (speedup 1.0000x reference)
; #define PG8_STAGE(bufoff, gbase, voff) do { _Pragma("unroll") for (int _i = 0; _i < 2; ++_i) \
;         __builtin_amdgcn_global_load_lds((const unsigned*)((const char*)(gbase) + (voff)[_i]), (PG8_LAS unsigned*)(lds + (bufoff) + ldsw + _i * 8192), 16, 0, 0); } while (0)
; #define PG8_LDA(dst, b, h) do { _Pragma("unroll") for (int m = 0; m < 4; ++m) _Pragma("unroll") for (int k = 0; k < 2; ++k) dst[m][k] = *(const PG8_LAS bf16x8*)(lds + PG8_SA(b, h) + aoff + m * 2048 + k * 1024); } while (0)
; #define PG8_LDB(dst, b, h) do { _Pragma("unroll") for (int n = 0; n < 2; ++n) _Pragma("unroll") for (int k = 0; k < 2; ++k) dst[n][k] = *(const PG8_LAS bf16x8*)(lds + PG8_SB(b, h) + boff + n * 2048 + k * 1024); } while (0)
; #define PG8_MMA(ai, bj, At, Bt) do { __builtin_amdgcn_s_setprio(1); _Pragma("unroll") for (int m = 0; m < 4; ++m) _Pragma("unroll") for (int n = 0; n < 2; ++n) _Pragma("unroll") for (int k = 0; k < 2; ++k) \
;         acc[ai][bj][m][n] = __builtin_amdgcn_mfma_f32_16x16x32_bf16(Bt[n][k], At[m][k], acc[ai][bj][m][n], 0, 0, 0); __builtin_amdgcn_s_setprio(0); } while (0)
; #define PG8_WAIT_V(n) asm volatile("s_waitcnt vmcnt(" #n ")" ::: "memory")
; #define PG8_WAIT_L(n) asm volatile("s_waitcnt lgkmcnt(" #n ")" ::: "memory")
; #define PG8_BAR __builtin_amdgcn_s_barrier()
; #define PG8_SCHED __builtin_amdgcn_sched_barrier(0)
; template <class Epi, class Sched, bool ALIGN_EPI = false, bool SP2 = false>
; __device__ __forceinline__ void gemm_phase(PG8_LAS unsigned char* lds, const Gemm g, const Sched& S, const Epi& E) {
;     ...
;             PG8_LDB(B0, 0, 0); PG8_LDB(B1, 0, 1); PG8_SCHED; PG8_LDA(At, 0, 0); PG8_STAGE(PG8_SA(1, 1), a1 + hstep, voffA);
;             PG8_WAIT_V(8); PG8_WAIT_L(0); PG8_BAR; PG8_MMA(0, 0, At, B0); PG8_MMA(0, 1, At, B1); PG8_BAR; PG8_SCHED;
;             PG8_LDA(At, 0, 1); PG8_STAGE(PG8_SB(0, 0), b2, voffB); PG8_STAGE(PG8_SB(0, 1), b2 + hstep, voffB); PG8_STAGE(PG8_SA(0, 0), a2, voffA);
;             PG8_WAIT_V(8); PG8_WAIT_L(0); PG8_BAR; PG8_MMA(1, 0, At, B0); PG8_MMA(1, 1, At, B1); PG8_BAR; PG8_SCHED;
.LBB0_38:
	s_add_u32 s38, s36, 0x100
	s_addc_u32 s39, s37, 0
	s_add_i32 s47, 0, 0x10000
	s_cmp_eq_u32 s43, 28
	s_cselect_b32 s65, s9, s39
	s_cselect_b32 s64, s8, s38
	s_cselect_b32 s5, s19, s41
	s_cselect_b32 s4, s18, s31
	s_add_i32 s50, 0, 0x14000
	v_add_u32_e32 v156, s47, v1
	v_add_u32_e32 v172, s50, v1
	ds_read_b128 v[144:147], v156
	ds_read_b128 v[148:151], v156 offset:1024
	ds_read_b128 v[152:155], v156 offset:2048
	ds_read_b128 v[156:159], v156 offset:3072
	ds_read_b128 v[160:163], v172
	ds_read_b128 v[164:167], v172 offset:1024
	ds_read_b128 v[168:171], v172 offset:2048
	ds_read_b128 v[172:175], v172 offset:3072
	v_lshl_add_u64 v[208:209], s[36:37], 0, v[142:143]
	s_add_i32 m0, s54, 0xc000
	ds_read_b128 v[176:179], v17
	ds_read_b128 v[180:183], v17 offset:1024
	ds_read_b128 v[184:187], v17 offset:2048
	ds_read_b128 v[188:191], v17 offset:3072
	ds_read_b128 v[192:195], v17 offset:4096
	ds_read_b128 v[196:199], v17 offset:5120
	ds_read_b128 v[200:203], v17 offset:6144
	ds_read_b128 v[204:207], v17 offset:7168
	global_load_lds_dwordx4 v[208:209], off
	v_lshl_add_u64 v[208:209], s[36:37], 0, v[140:141]
	s_add_i32 m0, s54, 0xe000
	s_nop 0
	global_load_lds_dwordx4 v[208:209], off
	s_waitcnt vmcnt(8)
	s_waitcnt lgkmcnt(0)
	s_barrier
	s_setprio 1
	s_waitcnt lgkmcnt(0)
	v_mfma_f32_16x16x32_bf16 v[130:133], v[144:147], v[176:179], v[130:133]
	v_mfma_f32_16x16x32_bf16 v[126:129], v[152:155], v[176:179], v[126:129]
	v_mfma_f32_16x16x32_bf16 v[114:117], v[144:147], v[184:187], v[114:117]
	v_mfma_f32_16x16x32_bf16 v[110:113], v[152:155], v[184:187], v[110:113]
	v_mfma_f32_16x16x32_bf16 v[98:101], v[144:147], v[192:195], v[98:101]
	v_mfma_f32_16x16x32_bf16 v[94:97], v[152:155], v[192:195], v[94:97]
	v_mfma_f32_16x16x32_bf16 v[82:85], v[144:147], v[200:203], v[82:85]
	v_mfma_f32_16x16x32_bf16 v[78:81], v[152:155], v[200:203], v[78:81]
	v_mfma_f32_16x16x32_bf16 v[130:133], v[148:151], v[180:183], v[130:133]
	v_mfma_f32_16x16x32_bf16 v[126:129], v[156:159], v[180:183], v[126:129]
	v_mfma_f32_16x16x32_bf16 v[114:117], v[148:151], v[188:191], v[114:117]
	v_mfma_f32_16x16x32_bf16 v[110:113], v[156:159], v[188:191], v[110:113]
	v_mfma_f32_16x16x32_bf16 v[98:101], v[148:151], v[196:199], v[98:101]
	v_mfma_f32_16x16x32_bf16 v[94:97], v[156:159], v[196:199], v[94:97]
	v_mfma_f32_16x16x32_bf16 v[82:85], v[148:151], v[204:207], v[82:85]
	v_mfma_f32_16x16x32_bf16 v[78:81], v[156:159], v[204:207], v[78:81]
	v_mfma_f32_16x16x32_bf16 v[122:125], v[160:163], v[176:179], v[122:125]
	v_mfma_f32_16x16x32_bf16 v[118:121], v[168:171], v[176:179], v[118:121]
	v_mfma_f32_16x16x32_bf16 v[106:109], v[160:163], v[184:187], v[106:109]
	v_mfma_f32_16x16x32_bf16 v[102:105], v[168:171], v[184:187], v[102:105]
	v_mfma_f32_16x16x32_bf16 v[90:93], v[160:163], v[192:195], v[90:93]
	v_mfma_f32_16x16x32_bf16 v[86:89], v[168:171], v[192:195], v[86:89]
	v_mfma_f32_16x16x32_bf16 v[74:77], v[160:163], v[200:203], v[74:77]
	v_mfma_f32_16x16x32_bf16 v[70:73], v[168:171], v[200:203], v[70:73]
	v_mfma_f32_16x16x32_bf16 v[122:125], v[164:167], v[180:183], v[122:125]
	v_mfma_f32_16x16x32_bf16 v[118:121], v[172:175], v[180:183], v[118:121]
	v_mfma_f32_16x16x32_bf16 v[106:109], v[164:167], v[188:191], v[106:109]
	v_mfma_f32_16x16x32_bf16 v[102:105], v[172:175], v[188:191], v[102:105]
	v_mfma_f32_16x16x32_bf16 v[90:93], v[164:167], v[196:199], v[90:93]
	v_mfma_f32_16x16x32_bf16 v[86:89], v[172:175], v[196:199], v[86:89]
	v_mfma_f32_16x16x32_bf16 v[74:77], v[164:167], v[204:207], v[74:77]
	v_mfma_f32_16x16x32_bf16 v[70:73], v[172:175], v[204:207], v[70:73]
	s_setprio 0
	s_barrier
	s_add_i32 s36, s47, s46
	v_lshl_add_u64 v[208:209], s[4:5], 0, v[136:137]
	s_mov_b32 m0, s36
	ds_read_b128 v[176:179], v17 offset:16384
	ds_read_b128 v[180:183], v17 offset:17408
	ds_read_b128 v[184:187], v17 offset:18432
	ds_read_b128 v[188:191], v17 offset:19456
	ds_read_b128 v[192:195], v17 offset:20480
	ds_read_b128 v[196:199], v17 offset:21504
	ds_read_b128 v[200:203], v17 offset:22528
	ds_read_b128 v[204:207], v17 offset:23552
	global_load_lds_dwordx4 v[208:209], off
	s_add_i32 m0, s36, 0x2000
	s_add_u32 s36, s4, 0x84000
	v_lshl_add_u64 v[214:215], s[4:5], 0, v[14:15]
	s_addc_u32 s37, s5, 0
	s_add_i32 s47, s50, s46
	global_load_lds_dwordx4 v[214:215], off
	v_lshl_add_u64 v[216:217], s[36:37], 0, v[136:137]
	s_mov_b32 m0, s47
	v_lshl_add_u64 v[220:221], s[64:65], 0, v[134:135]
	global_load_lds_dwordx4 v[216:217], off
	v_lshl_add_u64 v[216:217], s[36:37], 0, v[14:15]
	s_add_i32 m0, s47, 0x2000
	s_nop 0
	global_load_lds_dwordx4 v[216:217], off
	v_lshl_add_u64 v[216:217], s[64:65], 0, v[138:139]
	s_mov_b32 m0, s54
	s_nop 0
	global_load_lds_dwordx4 v[216:217], off
	s_mov_b32 m0, s68
	s_nop 0
	global_load_lds_dwordx4 v[220:221], off
	s_waitcnt vmcnt(8)
	s_waitcnt lgkmcnt(0)
	s_barrier
; #define PG8_STAGE(bufoff, gbase, voff) do { _Pragma("unroll") for (int _i = 0; _i < 2; ++_i) \
;         __builtin_amdgcn_global_load_lds((const unsigned*)((const char*)(gbase) + (voff)[_i]), (PG8_LAS unsigned*)(lds + (bufoff) + ldsw + _i * 8192), 16, 0, 0); } while (0)
; #define PG8_LDA(dst, b, h) do { _Pragma("unroll") for (int m = 0; m < 4; ++m) _Pragma("unroll") for (int k = 0; k < 2; ++k) dst[m][k] = *(const PG8_LAS bf16x8*)(lds + PG8_SA(b, h) + aoff + m * 2048 + k * 1024); } while (0)
; #define PG8_LDB(dst, b, h) do { _Pragma("unroll") for (int n = 0; n < 2; ++n) _Pragma("unroll") for (int k = 0; k < 2; ++k) dst[n][k] = *(const PG8_LAS bf16x8*)(lds + PG8_SB(b, h) + boff + n * 2048 + k * 1024); } while (0)
; #define PG8_MMA(ai, bj, At, Bt) do { __builtin_amdgcn_s_setprio(1); _Pragma("unroll") for (int m = 0; m < 4; ++m) _Pragma("unroll") for (int n = 0; n < 2; ++n) _Pragma("unroll") for (int k = 0; k < 2; ++k) \
;         acc[ai][bj][m][n] = __builtin_amdgcn_mfma_f32_16x16x32_bf16(Bt[n][k], At[m][k], acc[ai][bj][m][n], 0, 0, 0); __builtin_amdgcn_s_setprio(0); } while (0)
; #define PG8_WAIT_V(n) asm volatile("s_waitcnt vmcnt(" #n ")" ::: "memory")
; #define PG8_WAIT_L(n) asm volatile("s_waitcnt lgkmcnt(" #n ")" ::: "memory")
; #define PG8_BAR __builtin_amdgcn_s_barrier()
; #define PG8_SCHED __builtin_amdgcn_sched_barrier(0)
; template <class Epi, class Sched, bool ALIGN_EPI = false, bool SP2 = false>
; __device__ __forceinline__ void gemm_phase(PG8_LAS unsigned char* lds, const Gemm g, const Sched& S, const Epi& E) {
;     ...
;             PG8_WAIT_V(8); PG8_WAIT_L(0); PG8_BAR; PG8_MMA(1, 0, At, B0); PG8_MMA(1, 1, At, B1); PG8_BAR; PG8_SCHED;
;             PG8_LDB(B0, 1, 0); PG8_LDB(B1, 1, 1); PG8_SCHED; PG8_LDA(At, 1, 0); PG8_STAGE(PG8_SA(0, 1), a2 + hstep, voffA);
;             PG8_WAIT_V(8); PG8_WAIT_L(0); PG8_BAR; PG8_MMA(0, 0, At, B0); PG8_MMA(0, 1, At, B1); PG8_BAR; PG8_SCHED;
	s_setprio 1
	s_waitcnt lgkmcnt(0)
	v_mfma_f32_16x16x32_bf16 v[66:69], v[144:147], v[176:179], v[66:69]
	v_mfma_f32_16x16x32_bf16 v[62:65], v[152:155], v[176:179], v[62:65]
	v_mfma_f32_16x16x32_bf16 v[50:53], v[144:147], v[184:187], v[50:53]
	v_mfma_f32_16x16x32_bf16 v[46:49], v[152:155], v[184:187], v[46:49]
	v_mfma_f32_16x16x32_bf16 v[34:37], v[144:147], v[192:195], v[34:37]
	v_mfma_f32_16x16x32_bf16 v[30:33], v[152:155], v[192:195], v[30:33]
	v_mfma_f32_16x16x32_bf16 v[18:21], v[144:147], v[200:203], v[18:21]
	v_mfma_f32_16x16x32_bf16 v[10:13], v[152:155], v[200:203], v[10:13]
	v_mfma_f32_16x16x32_bf16 v[66:69], v[148:151], v[180:183], v[66:69]
	v_mfma_f32_16x16x32_bf16 v[62:65], v[156:159], v[180:183], v[62:65]
	v_mfma_f32_16x16x32_bf16 v[50:53], v[148:151], v[188:191], v[50:53]
	v_mfma_f32_16x16x32_bf16 v[46:49], v[156:159], v[188:191], v[46:49]
	v_mfma_f32_16x16x32_bf16 v[34:37], v[148:151], v[196:199], v[34:37]
	v_mfma_f32_16x16x32_bf16 v[30:33], v[156:159], v[196:199], v[30:33]
	v_mfma_f32_16x16x32_bf16 v[18:21], v[148:151], v[204:207], v[18:21]
	v_mfma_f32_16x16x32_bf16 v[10:13], v[156:159], v[204:207], v[10:13]
	v_mfma_f32_16x16x32_bf16 v[58:61], v[160:163], v[176:179], v[58:61]
	v_mfma_f32_16x16x32_bf16 v[54:57], v[168:171], v[176:179], v[54:57]
	v_mfma_f32_16x16x32_bf16 v[42:45], v[160:163], v[184:187], v[42:45]
	v_mfma_f32_16x16x32_bf16 v[38:41], v[168:171], v[184:187], v[38:41]
	v_mfma_f32_16x16x32_bf16 v[26:29], v[160:163], v[192:195], v[26:29]
	v_mfma_f32_16x16x32_bf16 v[22:25], v[168:171], v[192:195], v[22:25]
	v_mfma_f32_16x16x32_bf16 v[6:9], v[160:163], v[200:203], v[6:9]
	v_mfma_f32_16x16x32_bf16 v[2:5], v[168:171], v[200:203], v[2:5]
	v_mfma_f32_16x16x32_bf16 v[58:61], v[164:167], v[180:183], v[58:61]
	v_mfma_f32_16x16x32_bf16 v[54:57], v[172:175], v[180:183], v[54:57]
	v_mfma_f32_16x16x32_bf16 v[42:45], v[164:167], v[188:191], v[42:45]
	v_mfma_f32_16x16x32_bf16 v[38:41], v[172:175], v[188:191], v[38:41]
	v_mfma_f32_16x16x32_bf16 v[26:29], v[164:167], v[196:199], v[26:29]
	v_mfma_f32_16x16x32_bf16 v[22:25], v[172:175], v[196:199], v[22:25]
	v_mfma_f32_16x16x32_bf16 v[6:9], v[164:167], v[204:207], v[6:9]
	v_mfma_f32_16x16x32_bf16 v[2:5], v[172:175], v[204:207], v[2:5]
	s_setprio 0
	s_barrier
	s_add_i32 s47, 0, 0x18000
	s_add_i32 s50, 0, 0x1c000
	v_add_u32_e32 v156, s47, v1
	v_add_u32_e32 v172, s50, v1
	ds_read_b128 v[144:147], v156
	ds_read_b128 v[148:151], v156 offset:1024
	ds_read_b128 v[152:155], v156 offset:2048
	ds_read_b128 v[156:159], v156 offset:3072
	ds_read_b128 v[160:163], v172
	ds_read_b128 v[164:167], v172 offset:1024
	ds_read_b128 v[168:171], v172 offset:2048
	ds_read_b128 v[172:175], v172 offset:3072
	s_add_u32 s36, s64, 0x84000
	s_addc_u32 s37, s65, 0
	s_mov_b32 m0, s77
	v_lshl_add_u64 v[222:223], s[36:37], 0, v[138:139]
	ds_read_b128 v[176:179], v17 offset:32768
	ds_read_b128 v[180:183], v17 offset:33792
	ds_read_b128 v[184:187], v17 offset:34816
	ds_read_b128 v[188:191], v17 offset:35840
	ds_read_b128 v[192:195], v17 offset:36864
	ds_read_b128 v[196:199], v17 offset:37888
	ds_read_b128 v[200:203], v17 offset:38912
	ds_read_b128 v[204:207], v17 offset:39936
	global_load_lds_dwordx4 v[222:223], off
	v_lshl_add_u64 v[222:223], s[36:37], 0, v[134:135]
	s_mov_b32 m0, s84
	s_nop 0
	global_load_lds_dwordx4 v[222:223], off
	s_waitcnt vmcnt(8)
	s_waitcnt lgkmcnt(0)
	s_barrier
	s_setprio 1
	s_waitcnt lgkmcnt(0)
	v_mfma_f32_16x16x32_bf16 v[130:133], v[144:147], v[176:179], v[130:133]
	v_mfma_f32_16x16x32_bf16 v[126:129], v[152:155], v[176:179], v[126:129]
	v_mfma_f32_16x16x32_bf16 v[114:117], v[144:147], v[184:187], v[114:117]
	v_mfma_f32_16x16x32_bf16 v[110:113], v[152:155], v[184:187], v[110:113]
	v_mfma_f32_16x16x32_bf16 v[98:101], v[144:147], v[192:195], v[98:101]
	v_mfma_f32_16x16x32_bf16 v[94:97], v[152:155], v[192:195], v[94:97]
	v_mfma_f32_16x16x32_bf16 v[82:85], v[144:147], v[200:203], v[82:85]
	v_mfma_f32_16x16x32_bf16 v[78:81], v[152:155], v[200:203], v[78:81]
	v_mfma_f32_16x16x32_bf16 v[130:133], v[148:151], v[180:183], v[130:133]
	v_mfma_f32_16x16x32_bf16 v[126:129], v[156:159], v[180:183], v[126:129]
	v_mfma_f32_16x16x32_bf16 v[114:117], v[148:151], v[188:191], v[114:117]
	v_mfma_f32_16x16x32_bf16 v[110:113], v[156:159], v[188:191], v[110:113]
	v_mfma_f32_16x16x32_bf16 v[98:101], v[148:151], v[196:199], v[98:101]
	v_mfma_f32_16x16x32_bf16 v[94:97], v[156:159], v[196:199], v[94:97]
	v_mfma_f32_16x16x32_bf16 v[82:85], v[148:151], v[204:207], v[82:85]
	v_mfma_f32_16x16x32_bf16 v[78:81], v[156:159], v[204:207], v[78:81]
	v_mfma_f32_16x16x32_bf16 v[122:125], v[160:163], v[176:179], v[122:125]
	v_mfma_f32_16x16x32_bf16 v[118:121], v[168:171], v[176:179], v[118:121]
	v_mfma_f32_16x16x32_bf16 v[106:109], v[160:163], v[184:187], v[106:109]
	v_mfma_f32_16x16x32_bf16 v[102:105], v[168:171], v[184:187], v[102:105]
	v_mfma_f32_16x16x32_bf16 v[90:93], v[160:163], v[192:195], v[90:93]
	v_mfma_f32_16x16x32_bf16 v[86:89], v[168:171], v[192:195], v[86:89]
	v_mfma_f32_16x16x32_bf16 v[74:77], v[160:163], v[200:203], v[74:77]
	v_mfma_f32_16x16x32_bf16 v[70:73], v[168:171], v[200:203], v[70:73]
	v_mfma_f32_16x16x32_bf16 v[122:125], v[164:167], v[180:183], v[122:125]
	v_mfma_f32_16x16x32_bf16 v[118:121], v[172:175], v[180:183], v[118:121]
	v_mfma_f32_16x16x32_bf16 v[106:109], v[164:167], v[188:191], v[106:109]
	v_mfma_f32_16x16x32_bf16 v[102:105], v[172:175], v[188:191], v[102:105]
	v_mfma_f32_16x16x32_bf16 v[90:93], v[164:167], v[196:199], v[90:93]
	v_mfma_f32_16x16x32_bf16 v[86:89], v[172:175], v[196:199], v[86:89]
	v_mfma_f32_16x16x32_bf16 v[74:77], v[164:167], v[204:207], v[74:77]
	v_mfma_f32_16x16x32_bf16 v[70:73], v[172:175], v[204:207], v[70:73]
	s_setprio 0
	s_barrier
; #define PG8_STAGE(bufoff, gbase, voff) do { _Pragma("unroll") for (int _i = 0; _i < 2; ++_i) \
;         __builtin_amdgcn_global_load_lds((const unsigned*)((const char*)(gbase) + (voff)[_i]), (PG8_LAS unsigned*)(lds + (bufoff) + ldsw + _i * 8192), 16, 0, 0); } while (0)
; #define PG8_LDA(dst, b, h) do { _Pragma("unroll") for (int m = 0; m < 4; ++m) _Pragma("unroll") for (int k = 0; k < 2; ++k) dst[m][k] = *(const PG8_LAS bf16x8*)(lds + PG8_SA(b, h) + aoff + m * 2048 + k * 1024); } while (0)
; #define PG8_MMA(ai, bj, At, Bt) do { __builtin_amdgcn_s_setprio(1); _Pragma("unroll") for (int m = 0; m < 4; ++m) _Pragma("unroll") for (int n = 0; n < 2; ++n) _Pragma("unroll") for (int k = 0; k < 2; ++k) \
;         acc[ai][bj][m][n] = __builtin_amdgcn_mfma_f32_16x16x32_bf16(Bt[n][k], At[m][k], acc[ai][bj][m][n], 0, 0, 0); __builtin_amdgcn_s_setprio(0); } while (0)
; #define PG8_WAIT_V(n) asm volatile("s_waitcnt vmcnt(" #n ")" ::: "memory")
; #define PG8_WAIT_L(n) asm volatile("s_waitcnt lgkmcnt(" #n ")" ::: "memory")
; #define PG8_BAR __builtin_amdgcn_s_barrier()
; #define PG8_SCHED __builtin_amdgcn_sched_barrier(0)
; template <class Epi, class Sched, bool ALIGN_EPI = false, bool SP2 = false>
; __device__ __forceinline__ void gemm_phase(PG8_LAS unsigned char* lds, const Gemm g, const Sched& S, const Epi& E) {
;     ...
;         for (int t = 0; t < nt; t += 2) {
;             const bool last = (t == nt - 2);
;             const char* a1 = cA + (size_t)(t + 1) * kstep;
;             const char* a2 = last ? nA : cA + (size_t)(t + 2) * kstep; const char* b2 = last ? nB : cB + (size_t)(t + 2) * kstep;
;             const char* a3 = a2 + kstep; const char* b3 = b2 + kstep;
;     ...
;             PG8_LDA(At, 1, 1); PG8_STAGE(PG8_SB(1, 0), b3, voffB); PG8_STAGE(PG8_SB(1, 1), b3 + hstep, voffB); PG8_STAGE(PG8_SA(1, 0), a3, voffA);
;             PG8_WAIT_V(8); PG8_WAIT_L(0); PG8_BAR; PG8_MMA(1, 0, At, B0); PG8_MMA(1, 1, At, B1); PG8_BAR; PG8_SCHED;
	s_add_i32 s36, s47, s46
	v_lshl_add_u64 v[208:209], v[208:209], 0, s[48:49]
	s_mov_b32 m0, s36
	ds_read_b128 v[176:179], v17 offset:49152
	ds_read_b128 v[180:183], v17 offset:50176
	ds_read_b128 v[184:187], v17 offset:51200
	ds_read_b128 v[188:191], v17 offset:52224
	ds_read_b128 v[192:195], v17 offset:53248
	ds_read_b128 v[196:199], v17 offset:54272
	ds_read_b128 v[200:203], v17 offset:55296
	ds_read_b128 v[204:207], v17 offset:56320
	global_load_lds_dwordx4 v[208:209], off
	s_add_i32 m0, s36, 0x2000
	s_add_u32 s4, s4, 0x84080
	v_lshl_add_u64 v[208:209], v[214:215], 0, s[48:49]
	s_addc_u32 s5, s5, 0
	s_add_i32 s36, s50, s46
	global_load_lds_dwordx4 v[208:209], off
	v_lshl_add_u64 v[208:209], s[4:5], 0, v[136:137]
	s_mov_b32 m0, s36
	s_nop 0
	global_load_lds_dwordx4 v[208:209], off
	v_lshl_add_u64 v[208:209], s[4:5], 0, v[14:15]
	s_add_i32 m0, s36, 0x2000
	s_nop 0
	global_load_lds_dwordx4 v[208:209], off
	v_lshl_add_u64 v[208:209], v[216:217], 0, s[48:49]
	s_mov_b32 m0, s93
	s_nop 0
	global_load_lds_dwordx4 v[208:209], off
	v_lshl_add_u64 v[208:209], v[220:221], 0, s[48:49]
	s_mov_b32 m0, s94
	s_nop 0
	global_load_lds_dwordx4 v[208:209], off
	s_waitcnt vmcnt(8)
	s_waitcnt lgkmcnt(0)
	s_barrier
	s_setprio 1
	s_waitcnt lgkmcnt(0)
	v_mfma_f32_16x16x32_bf16 v[66:69], v[144:147], v[176:179], v[66:69]
	v_mfma_f32_16x16x32_bf16 v[62:65], v[152:155], v[176:179], v[62:65]
	v_mfma_f32_16x16x32_bf16 v[50:53], v[144:147], v[184:187], v[50:53]
	v_mfma_f32_16x16x32_bf16 v[46:49], v[152:155], v[184:187], v[46:49]
	v_mfma_f32_16x16x32_bf16 v[34:37], v[144:147], v[192:195], v[34:37]
	v_mfma_f32_16x16x32_bf16 v[30:33], v[152:155], v[192:195], v[30:33]
	v_mfma_f32_16x16x32_bf16 v[18:21], v[144:147], v[200:203], v[18:21]
	v_mfma_f32_16x16x32_bf16 v[10:13], v[152:155], v[200:203], v[10:13]
	v_mfma_f32_16x16x32_bf16 v[66:69], v[148:151], v[180:183], v[66:69]
	v_mfma_f32_16x16x32_bf16 v[62:65], v[156:159], v[180:183], v[62:65]
	v_mfma_f32_16x16x32_bf16 v[50:53], v[148:151], v[188:191], v[50:53]
	v_mfma_f32_16x16x32_bf16 v[46:49], v[156:159], v[188:191], v[46:49]
	v_mfma_f32_16x16x32_bf16 v[34:37], v[148:151], v[196:199], v[34:37]
	v_mfma_f32_16x16x32_bf16 v[30:33], v[156:159], v[196:199], v[30:33]
	v_mfma_f32_16x16x32_bf16 v[18:21], v[148:151], v[204:207], v[18:21]
	v_mfma_f32_16x16x32_bf16 v[10:13], v[156:159], v[204:207], v[10:13]
	v_mfma_f32_16x16x32_bf16 v[58:61], v[160:163], v[176:179], v[58:61]
	v_mfma_f32_16x16x32_bf16 v[54:57], v[168:171], v[176:179], v[54:57]
	v_mfma_f32_16x16x32_bf16 v[42:45], v[160:163], v[184:187], v[42:45]
	v_mfma_f32_16x16x32_bf16 v[38:41], v[168:171], v[184:187], v[38:41]
	v_mfma_f32_16x16x32_bf16 v[26:29], v[160:163], v[192:195], v[26:29]
	v_mfma_f32_16x16x32_bf16 v[22:25], v[168:171], v[192:195], v[22:25]
	v_mfma_f32_16x16x32_bf16 v[6:9], v[160:163], v[200:203], v[6:9]
	v_mfma_f32_16x16x32_bf16 v[2:5], v[168:171], v[200:203], v[2:5]
	v_mfma_f32_16x16x32_bf16 v[58:61], v[164:167], v[180:183], v[58:61]
	v_mfma_f32_16x16x32_bf16 v[54:57], v[172:175], v[180:183], v[54:57]
	v_mfma_f32_16x16x32_bf16 v[42:45], v[164:167], v[188:191], v[42:45]
	v_mfma_f32_16x16x32_bf16 v[38:41], v[172:175], v[188:191], v[38:41]
	v_mfma_f32_16x16x32_bf16 v[26:29], v[164:167], v[196:199], v[26:29]
	v_mfma_f32_16x16x32_bf16 v[22:25], v[172:175], v[196:199], v[22:25]
	v_mfma_f32_16x16x32_bf16 v[6:9], v[164:167], v[204:207], v[6:9]
	v_mfma_f32_16x16x32_bf16 v[2:5], v[172:175], v[204:207], v[2:5]
	s_setprio 0
	s_barrier
	s_add_i32 s43, s43, 2
	s_add_u32 s31, s31, 0x100
	s_addc_u32 s41, s41, 0
	s_cmp_gt_u32 s43, 29
	s_mov_b64 s[36:37], s[38:39]
	s_cbranch_scc0 .LBB0_38
	s_and_b64 vcc, exec, s[16:17]
	s_cbranch_vccz .LBB0_41
	s_barrier

; #define PG8_STAGE(bufoff, gbase, voff) do { _Pragma("unroll") for (int _i = 0; _i < 2; ++_i) \
;         __builtin_amdgcn_global_load_lds((const unsigned*)((const char*)(gbase) + (voff)[_i]), (PG8_LAS unsigned*)(lds + (bufoff) + ldsw + _i * 8192), 16, 0, 0); } while (0)
; #define PG8_LDA(dst, b, h) do { _Pragma("unroll") for (int m = 0; m < 4; ++m) _Pragma("unroll") for (int k = 0; k < 2; ++k) dst[m][k] = *(const PG8_LAS bf16x8*)(lds + PG8_SA(b, h) + aoff + m * 2048 + k * 1024); } while (0)
; #define PG8_LDB(dst, b, h) do { _Pragma("unroll") for (int n = 0; n < 2; ++n) _Pragma("unroll") for (int k = 0; k < 2; ++k) dst[n][k] = *(const PG8_LAS bf16x8*)(lds + PG8_SB(b, h) + boff + n * 2048 + k * 1024); } while (0)
; #define PG8_MMA(ai, bj, At, Bt) do { __builtin_amdgcn_s_setprio(1); _Pragma("unroll") for (int m = 0; m < 4; ++m) _Pragma("unroll") for (int n = 0; n < 2; ++n) _Pragma("unroll") for (int k = 0; k < 2; ++k) \
;         acc[ai][bj][m][n] = __builtin_amdgcn_mfma_f32_16x16x32_bf16(Bt[n][k], At[m][k], acc[ai][bj][m][n], 0, 0, 0); __builtin_amdgcn_s_setprio(0); } while (0)
; #define PG8_WAIT_V(n) asm volatile("s_waitcnt vmcnt(" #n ")" ::: "memory")
; #define PG8_WAIT_L(n) asm volatile("s_waitcnt lgkmcnt(" #n ")" ::: "memory")
; #define PG8_BAR __builtin_amdgcn_s_barrier()
; #define PG8_SCHED __builtin_amdgcn_sched_barrier(0)
; template <class Epi, class Sched, bool ALIGN_EPI = false, bool SP2 = false>
; __device__ __forceinline__ void gemm_phase(PG8_LAS unsigned char* lds, const Gemm g, const Sched& S, const Epi& E) {
;     ...
;             PG8_LDB(B0, 0, 0); PG8_LDB(B1, 0, 1); PG8_SCHED; PG8_LDA(At, 0, 0); PG8_STAGE(PG8_SA(1, 1), a1 + hstep, voffA);
;             PG8_WAIT_V(8); PG8_WAIT_L(0); PG8_BAR; PG8_MMA(0, 0, At, B0); PG8_MMA(0, 1, At, B1); PG8_BAR; PG8_SCHED;
;             PG8_LDA(At, 0, 1); PG8_STAGE(PG8_SB(0, 0), b2, voffB); PG8_STAGE(PG8_SB(0, 1), b2 + hstep, voffB); PG8_STAGE(PG8_SA(0, 0), a2, voffA);
;             PG8_WAIT_V(8); PG8_WAIT_L(0); PG8_BAR; PG8_MMA(1, 0, At, B0); PG8_MMA(1, 1, At, B1); PG8_BAR; PG8_SCHED;
.LBB0_314:
	s_add_u32 s8, s18, 0x100
	s_addc_u32 s9, s19, 0
	s_add_i32 s50, 0, 0x10000
	s_cmp_eq_u32 vcc_hi, 28
	s_cselect_b32 s37, s15, s9
	s_cselect_b32 s36, s14, s8
	s_cselect_b32 s5, s17, vcc_lo
	s_cselect_b32 s4, s16, s54
	s_add_i32 s51, 0, 0x14000
	v_add_u32_e32 v156, s50, v1
	v_add_u32_e32 v172, s51, v1
	ds_read_b128 v[144:147], v156
	ds_read_b128 v[148:151], v156 offset:1024
	ds_read_b128 v[152:155], v156 offset:2048
	ds_read_b128 v[156:159], v156 offset:3072
	ds_read_b128 v[160:163], v172
	ds_read_b128 v[164:167], v172 offset:1024
	ds_read_b128 v[168:171], v172 offset:2048
	ds_read_b128 v[172:175], v172 offset:3072
	v_lshl_add_u64 v[208:209], s[18:19], 0, v[142:143]
	s_add_i32 m0, s39, 0xc000
	ds_read_b128 v[176:179], v17
	ds_read_b128 v[180:183], v17 offset:1024
	ds_read_b128 v[184:187], v17 offset:2048
	ds_read_b128 v[188:191], v17 offset:3072
	ds_read_b128 v[192:195], v17 offset:4096
	ds_read_b128 v[196:199], v17 offset:5120
	ds_read_b128 v[200:203], v17 offset:6144
	ds_read_b128 v[204:207], v17 offset:7168
	global_load_lds_dwordx4 v[208:209], off
	v_lshl_add_u64 v[208:209], s[18:19], 0, v[140:141]
	s_add_i32 m0, s39, 0xe000
	s_nop 0
	global_load_lds_dwordx4 v[208:209], off
	s_waitcnt vmcnt(8)
	s_waitcnt lgkmcnt(0)
	s_barrier
	s_setprio 1
	s_waitcnt lgkmcnt(0)
	v_mfma_f32_16x16x32_bf16 v[130:133], v[144:147], v[176:179], v[130:133]
	v_mfma_f32_16x16x32_bf16 v[102:105], v[152:155], v[176:179], v[102:105]
	v_mfma_f32_16x16x32_bf16 v[126:129], v[144:147], v[184:187], v[126:129]
	v_mfma_f32_16x16x32_bf16 v[94:97], v[152:155], v[184:187], v[94:97]
	v_mfma_f32_16x16x32_bf16 v[122:125], v[144:147], v[192:195], v[122:125]
	v_mfma_f32_16x16x32_bf16 v[90:93], v[152:155], v[192:195], v[90:93]
	v_mfma_f32_16x16x32_bf16 v[118:121], v[144:147], v[200:203], v[118:121]
	v_mfma_f32_16x16x32_bf16 v[86:89], v[152:155], v[200:203], v[86:89]
	v_mfma_f32_16x16x32_bf16 v[130:133], v[148:151], v[180:183], v[130:133]
	v_mfma_f32_16x16x32_bf16 v[102:105], v[156:159], v[180:183], v[102:105]
	v_mfma_f32_16x16x32_bf16 v[126:129], v[148:151], v[188:191], v[126:129]
	v_mfma_f32_16x16x32_bf16 v[94:97], v[156:159], v[188:191], v[94:97]
	v_mfma_f32_16x16x32_bf16 v[122:125], v[148:151], v[196:199], v[122:125]
	v_mfma_f32_16x16x32_bf16 v[90:93], v[156:159], v[196:199], v[90:93]
	v_mfma_f32_16x16x32_bf16 v[118:121], v[148:151], v[204:207], v[118:121]
	v_mfma_f32_16x16x32_bf16 v[86:89], v[156:159], v[204:207], v[86:89]
	v_mfma_f32_16x16x32_bf16 v[66:69], v[160:163], v[176:179], v[66:69]
	v_mfma_f32_16x16x32_bf16 v[38:41], v[168:171], v[176:179], v[38:41]
	v_mfma_f32_16x16x32_bf16 v[62:65], v[160:163], v[184:187], v[62:65]
	v_mfma_f32_16x16x32_bf16 v[30:33], v[168:171], v[184:187], v[30:33]
	v_mfma_f32_16x16x32_bf16 v[58:61], v[160:163], v[192:195], v[58:61]
	v_mfma_f32_16x16x32_bf16 v[26:29], v[168:171], v[192:195], v[26:29]
	v_mfma_f32_16x16x32_bf16 v[54:57], v[160:163], v[200:203], v[54:57]
	v_mfma_f32_16x16x32_bf16 v[22:25], v[168:171], v[200:203], v[22:25]
	v_mfma_f32_16x16x32_bf16 v[66:69], v[164:167], v[180:183], v[66:69]
	v_mfma_f32_16x16x32_bf16 v[38:41], v[172:175], v[180:183], v[38:41]
	v_mfma_f32_16x16x32_bf16 v[62:65], v[164:167], v[188:191], v[62:65]
	v_mfma_f32_16x16x32_bf16 v[30:33], v[172:175], v[188:191], v[30:33]
	v_mfma_f32_16x16x32_bf16 v[58:61], v[164:167], v[196:199], v[58:61]
	v_mfma_f32_16x16x32_bf16 v[26:29], v[172:175], v[196:199], v[26:29]
	v_mfma_f32_16x16x32_bf16 v[54:57], v[164:167], v[204:207], v[54:57]
	v_mfma_f32_16x16x32_bf16 v[22:25], v[172:175], v[204:207], v[22:25]
	s_setprio 0
	s_barrier
	s_add_i32 s18, s50, s38
	v_lshl_add_u64 v[208:209], s[4:5], 0, v[136:137]
	s_mov_b32 m0, s18
	ds_read_b128 v[176:179], v17 offset:16384
	ds_read_b128 v[180:183], v17 offset:17408
	ds_read_b128 v[184:187], v17 offset:18432
	ds_read_b128 v[188:191], v17 offset:19456
	ds_read_b128 v[192:195], v17 offset:20480
	ds_read_b128 v[196:199], v17 offset:21504
	ds_read_b128 v[200:203], v17 offset:22528
	ds_read_b128 v[204:207], v17 offset:23552
	global_load_lds_dwordx4 v[208:209], off
	s_add_i32 m0, s18, 0x2000
	s_add_u32 s18, s4, 0x84000
	v_lshl_add_u64 v[214:215], s[4:5], 0, v[14:15]
	s_addc_u32 s19, s5, 0
	s_add_i32 s50, s51, s38
	global_load_lds_dwordx4 v[214:215], off
	v_lshl_add_u64 v[216:217], s[18:19], 0, v[136:137]
	s_mov_b32 m0, s50
	v_lshl_add_u64 v[220:221], s[36:37], 0, v[134:135]
	global_load_lds_dwordx4 v[216:217], off
	v_lshl_add_u64 v[216:217], s[18:19], 0, v[14:15]
	s_add_i32 m0, s50, 0x2000
	s_nop 0
	global_load_lds_dwordx4 v[216:217], off
	v_lshl_add_u64 v[216:217], s[36:37], 0, v[138:139]
	s_mov_b32 m0, s39
	s_nop 0
	global_load_lds_dwordx4 v[216:217], off
	s_mov_b32 m0, s46
	s_nop 0
	global_load_lds_dwordx4 v[220:221], off
	s_waitcnt vmcnt(8)
	s_waitcnt lgkmcnt(0)
	s_barrier
; #define PG8_STAGE(bufoff, gbase, voff) do { _Pragma("unroll") for (int _i = 0; _i < 2; ++_i) \
;         __builtin_amdgcn_global_load_lds((const unsigned*)((const char*)(gbase) + (voff)[_i]), (PG8_LAS unsigned*)(lds + (bufoff) + ldsw + _i * 8192), 16, 0, 0); } while (0)
; #define PG8_LDA(dst, b, h) do { _Pragma("unroll") for (int m = 0; m < 4; ++m) _Pragma("unroll") for (int k = 0; k < 2; ++k) dst[m][k] = *(const PG8_LAS bf16x8*)(lds + PG8_SA(b, h) + aoff + m * 2048 + k * 1024); } while (0)
; #define PG8_LDB(dst, b, h) do { _Pragma("unroll") for (int n = 0; n < 2; ++n) _Pragma("unroll") for (int k = 0; k < 2; ++k) dst[n][k] = *(const PG8_LAS bf16x8*)(lds + PG8_SB(b, h) + boff + n * 2048 + k * 1024); } while (0)
; #define PG8_MMA(ai, bj, At, Bt) do { __builtin_amdgcn_s_setprio(1); _Pragma("unroll") for (int m = 0; m < 4; ++m) _Pragma("unroll") for (int n = 0; n < 2; ++n) _Pragma("unroll") for (int k = 0; k < 2; ++k) \
;         acc[ai][bj][m][n] = __builtin_amdgcn_mfma_f32_16x16x32_bf16(Bt[n][k], At[m][k], acc[ai][bj][m][n], 0, 0, 0); __builtin_amdgcn_s_setprio(0); } while (0)
; #define PG8_WAIT_V(n) asm volatile("s_waitcnt vmcnt(" #n ")" ::: "memory")
; #define PG8_WAIT_L(n) asm volatile("s_waitcnt lgkmcnt(" #n ")" ::: "memory")
; #define PG8_BAR __builtin_amdgcn_s_barrier()
; #define PG8_SCHED __builtin_amdgcn_sched_barrier(0)
; template <class Epi, class Sched, bool ALIGN_EPI = false, bool SP2 = false>
; __device__ __forceinline__ void gemm_phase(PG8_LAS unsigned char* lds, const Gemm g, const Sched& S, const Epi& E) {
;     ...
;             PG8_WAIT_V(8); PG8_WAIT_L(0); PG8_BAR; PG8_MMA(1, 0, At, B0); PG8_MMA(1, 1, At, B1); PG8_BAR; PG8_SCHED;
;             PG8_LDB(B0, 1, 0); PG8_LDB(B1, 1, 1); PG8_SCHED; PG8_LDA(At, 1, 0); PG8_STAGE(PG8_SA(0, 1), a2 + hstep, voffA);
;             PG8_WAIT_V(8); PG8_WAIT_L(0); PG8_BAR; PG8_MMA(0, 0, At, B0); PG8_MMA(0, 1, At, B1); PG8_BAR; PG8_SCHED;
	s_setprio 1
	s_waitcnt lgkmcnt(0)
	v_mfma_f32_16x16x32_bf16 v[114:117], v[144:147], v[176:179], v[114:117]
	v_mfma_f32_16x16x32_bf16 v[82:85], v[152:155], v[176:179], v[82:85]
	v_mfma_f32_16x16x32_bf16 v[110:113], v[144:147], v[184:187], v[110:113]
	v_mfma_f32_16x16x32_bf16 v[78:81], v[152:155], v[184:187], v[78:81]
	v_mfma_f32_16x16x32_bf16 v[106:109], v[144:147], v[192:195], v[106:109]
	v_mfma_f32_16x16x32_bf16 v[74:77], v[152:155], v[192:195], v[74:77]
	v_mfma_f32_16x16x32_bf16 v[98:101], v[144:147], v[200:203], v[98:101]
	v_mfma_f32_16x16x32_bf16 v[70:73], v[152:155], v[200:203], v[70:73]
	v_mfma_f32_16x16x32_bf16 v[114:117], v[148:151], v[180:183], v[114:117]
	v_mfma_f32_16x16x32_bf16 v[82:85], v[156:159], v[180:183], v[82:85]
	v_mfma_f32_16x16x32_bf16 v[110:113], v[148:151], v[188:191], v[110:113]
	v_mfma_f32_16x16x32_bf16 v[78:81], v[156:159], v[188:191], v[78:81]
	v_mfma_f32_16x16x32_bf16 v[106:109], v[148:151], v[196:199], v[106:109]
	v_mfma_f32_16x16x32_bf16 v[74:77], v[156:159], v[196:199], v[74:77]
	v_mfma_f32_16x16x32_bf16 v[98:101], v[148:151], v[204:207], v[98:101]
	v_mfma_f32_16x16x32_bf16 v[70:73], v[156:159], v[204:207], v[70:73]
	v_mfma_f32_16x16x32_bf16 v[50:53], v[160:163], v[176:179], v[50:53]
	v_mfma_f32_16x16x32_bf16 v[18:21], v[168:171], v[176:179], v[18:21]
	v_mfma_f32_16x16x32_bf16 v[46:49], v[160:163], v[184:187], v[46:49]
	v_mfma_f32_16x16x32_bf16 v[10:13], v[168:171], v[184:187], v[10:13]
	v_mfma_f32_16x16x32_bf16 v[42:45], v[160:163], v[192:195], v[42:45]
	v_mfma_f32_16x16x32_bf16 v[6:9], v[168:171], v[192:195], v[6:9]
	v_mfma_f32_16x16x32_bf16 v[34:37], v[160:163], v[200:203], v[34:37]
	v_mfma_f32_16x16x32_bf16 v[2:5], v[168:171], v[200:203], v[2:5]
	v_mfma_f32_16x16x32_bf16 v[50:53], v[164:167], v[180:183], v[50:53]
	v_mfma_f32_16x16x32_bf16 v[18:21], v[172:175], v[180:183], v[18:21]
	v_mfma_f32_16x16x32_bf16 v[46:49], v[164:167], v[188:191], v[46:49]
	v_mfma_f32_16x16x32_bf16 v[10:13], v[172:175], v[188:191], v[10:13]
	v_mfma_f32_16x16x32_bf16 v[42:45], v[164:167], v[196:199], v[42:45]
	v_mfma_f32_16x16x32_bf16 v[6:9], v[172:175], v[196:199], v[6:9]
	v_mfma_f32_16x16x32_bf16 v[34:37], v[164:167], v[204:207], v[34:37]
	v_mfma_f32_16x16x32_bf16 v[2:5], v[172:175], v[204:207], v[2:5]
	s_setprio 0
	s_barrier
	s_add_i32 s50, 0, 0x18000
	s_add_i32 s51, 0, 0x1c000
	v_add_u32_e32 v156, s50, v1
	v_add_u32_e32 v172, s51, v1
	ds_read_b128 v[144:147], v156
	ds_read_b128 v[148:151], v156 offset:1024
	ds_read_b128 v[152:155], v156 offset:2048
	ds_read_b128 v[156:159], v156 offset:3072
	ds_read_b128 v[160:163], v172
	ds_read_b128 v[164:167], v172 offset:1024
	ds_read_b128 v[168:171], v172 offset:2048
	ds_read_b128 v[172:175], v172 offset:3072
	s_add_u32 s18, s36, 0x84000
	s_addc_u32 s19, s37, 0
	s_mov_b32 m0, s64
	v_lshl_add_u64 v[222:223], s[18:19], 0, v[138:139]
	ds_read_b128 v[176:179], v17 offset:32768
	ds_read_b128 v[180:183], v17 offset:33792
	ds_read_b128 v[184:187], v17 offset:34816
	ds_read_b128 v[188:191], v17 offset:35840
	ds_read_b128 v[192:195], v17 offset:36864
	ds_read_b128 v[196:199], v17 offset:37888
	ds_read_b128 v[200:203], v17 offset:38912
	ds_read_b128 v[204:207], v17 offset:39936
	global_load_lds_dwordx4 v[222:223], off
	v_lshl_add_u64 v[222:223], s[18:19], 0, v[134:135]
	s_mov_b32 m0, s65
	s_nop 0
	global_load_lds_dwordx4 v[222:223], off
	s_waitcnt vmcnt(8)
	s_waitcnt lgkmcnt(0)
	s_barrier
	s_setprio 1
	s_waitcnt lgkmcnt(0)
	v_mfma_f32_16x16x32_bf16 v[130:133], v[144:147], v[176:179], v[130:133]
	v_mfma_f32_16x16x32_bf16 v[102:105], v[152:155], v[176:179], v[102:105]
	v_mfma_f32_16x16x32_bf16 v[126:129], v[144:147], v[184:187], v[126:129]
	v_mfma_f32_16x16x32_bf16 v[94:97], v[152:155], v[184:187], v[94:97]
	v_mfma_f32_16x16x32_bf16 v[122:125], v[144:147], v[192:195], v[122:125]
	v_mfma_f32_16x16x32_bf16 v[90:93], v[152:155], v[192:195], v[90:93]
	v_mfma_f32_16x16x32_bf16 v[118:121], v[144:147], v[200:203], v[118:121]
	v_mfma_f32_16x16x32_bf16 v[86:89], v[152:155], v[200:203], v[86:89]
	v_mfma_f32_16x16x32_bf16 v[130:133], v[148:151], v[180:183], v[130:133]
	v_mfma_f32_16x16x32_bf16 v[102:105], v[156:159], v[180:183], v[102:105]
	v_mfma_f32_16x16x32_bf16 v[126:129], v[148:151], v[188:191], v[126:129]
	v_mfma_f32_16x16x32_bf16 v[94:97], v[156:159], v[188:191], v[94:97]
	v_mfma_f32_16x16x32_bf16 v[122:125], v[148:151], v[196:199], v[122:125]
	v_mfma_f32_16x16x32_bf16 v[90:93], v[156:159], v[196:199], v[90:93]
	v_mfma_f32_16x16x32_bf16 v[118:121], v[148:151], v[204:207], v[118:121]
	v_mfma_f32_16x16x32_bf16 v[86:89], v[156:159], v[204:207], v[86:89]
	v_mfma_f32_16x16x32_bf16 v[66:69], v[160:163], v[176:179], v[66:69]
	v_mfma_f32_16x16x32_bf16 v[38:41], v[168:171], v[176:179], v[38:41]
	v_mfma_f32_16x16x32_bf16 v[62:65], v[160:163], v[184:187], v[62:65]
	v_mfma_f32_16x16x32_bf16 v[30:33], v[168:171], v[184:187], v[30:33]
	v_mfma_f32_16x16x32_bf16 v[58:61], v[160:163], v[192:195], v[58:61]
	v_mfma_f32_16x16x32_bf16 v[26:29], v[168:171], v[192:195], v[26:29]
	v_mfma_f32_16x16x32_bf16 v[54:57], v[160:163], v[200:203], v[54:57]
	v_mfma_f32_16x16x32_bf16 v[22:25], v[168:171], v[200:203], v[22:25]
	v_mfma_f32_16x16x32_bf16 v[66:69], v[164:167], v[180:183], v[66:69]
	v_mfma_f32_16x16x32_bf16 v[38:41], v[172:175], v[180:183], v[38:41]
	v_mfma_f32_16x16x32_bf16 v[62:65], v[164:167], v[188:191], v[62:65]
	v_mfma_f32_16x16x32_bf16 v[30:33], v[172:175], v[188:191], v[30:33]
	v_mfma_f32_16x16x32_bf16 v[58:61], v[164:167], v[196:199], v[58:61]
	v_mfma_f32_16x16x32_bf16 v[26:29], v[172:175], v[196:199], v[26:29]
	v_mfma_f32_16x16x32_bf16 v[54:57], v[164:167], v[204:207], v[54:57]
	v_mfma_f32_16x16x32_bf16 v[22:25], v[172:175], v[204:207], v[22:25]
	s_setprio 0
	s_barrier
; #define PG8_STAGE(bufoff, gbase, voff) do { _Pragma("unroll") for (int _i = 0; _i < 2; ++_i) \
;         __builtin_amdgcn_global_load_lds((const unsigned*)((const char*)(gbase) + (voff)[_i]), (PG8_LAS unsigned*)(lds + (bufoff) + ldsw + _i * 8192), 16, 0, 0); } while (0)
; #define PG8_LDA(dst, b, h) do { _Pragma("unroll") for (int m = 0; m < 4; ++m) _Pragma("unroll") for (int k = 0; k < 2; ++k) dst[m][k] = *(const PG8_LAS bf16x8*)(lds + PG8_SA(b, h) + aoff + m * 2048 + k * 1024); } while (0)
; #define PG8_MMA(ai, bj, At, Bt) do { __builtin_amdgcn_s_setprio(1); _Pragma("unroll") for (int m = 0; m < 4; ++m) _Pragma("unroll") for (int n = 0; n < 2; ++n) _Pragma("unroll") for (int k = 0; k < 2; ++k) \
;         acc[ai][bj][m][n] = __builtin_amdgcn_mfma_f32_16x16x32_bf16(Bt[n][k], At[m][k], acc[ai][bj][m][n], 0, 0, 0); __builtin_amdgcn_s_setprio(0); } while (0)
; #define PG8_WAIT_V(n) asm volatile("s_waitcnt vmcnt(" #n ")" ::: "memory")
; #define PG8_WAIT_L(n) asm volatile("s_waitcnt lgkmcnt(" #n ")" ::: "memory")
; #define PG8_BAR __builtin_amdgcn_s_barrier()
; #define PG8_SCHED __builtin_amdgcn_sched_barrier(0)
; template <class Epi, class Sched, bool ALIGN_EPI = false, bool SP2 = false>
; __device__ __forceinline__ void gemm_phase(PG8_LAS unsigned char* lds, const Gemm g, const Sched& S, const Epi& E) {
;     ...
;         for (int t = 0; t < nt; t += 2) {
;             const bool last = (t == nt - 2);
;             const char* a1 = cA + (size_t)(t + 1) * kstep;
;             const char* a2 = last ? nA : cA + (size_t)(t + 2) * kstep; const char* b2 = last ? nB : cB + (size_t)(t + 2) * kstep;
;             const char* a3 = a2 + kstep; const char* b3 = b2 + kstep;
;     ...
;             PG8_LDA(At, 1, 1); PG8_STAGE(PG8_SB(1, 0), b3, voffB); PG8_STAGE(PG8_SB(1, 1), b3 + hstep, voffB); PG8_STAGE(PG8_SA(1, 0), a3, voffA);
;             PG8_WAIT_V(8); PG8_WAIT_L(0); PG8_BAR; PG8_MMA(1, 0, At, B0); PG8_MMA(1, 1, At, B1); PG8_BAR; PG8_SCHED;
	s_add_i32 s18, s50, s38
	v_lshl_add_u64 v[208:209], v[208:209], 0, s[48:49]
	s_mov_b32 m0, s18
	ds_read_b128 v[176:179], v17 offset:49152
	ds_read_b128 v[180:183], v17 offset:50176
	ds_read_b128 v[184:187], v17 offset:51200
	ds_read_b128 v[188:191], v17 offset:52224
	ds_read_b128 v[192:195], v17 offset:53248
	ds_read_b128 v[196:199], v17 offset:54272
	ds_read_b128 v[200:203], v17 offset:55296
	ds_read_b128 v[204:207], v17 offset:56320
	global_load_lds_dwordx4 v[208:209], off
	s_add_i32 m0, s18, 0x2000
	s_add_u32 s4, s4, 0x84080
	v_lshl_add_u64 v[208:209], v[214:215], 0, s[48:49]
	s_addc_u32 s5, s5, 0
	s_add_i32 s18, s51, s38
	global_load_lds_dwordx4 v[208:209], off
	v_lshl_add_u64 v[208:209], s[4:5], 0, v[136:137]
	s_mov_b32 m0, s18
	s_nop 0
	global_load_lds_dwordx4 v[208:209], off
	v_lshl_add_u64 v[208:209], s[4:5], 0, v[14:15]
	s_add_i32 m0, s18, 0x2000
	s_nop 0
	global_load_lds_dwordx4 v[208:209], off
	v_lshl_add_u64 v[208:209], v[216:217], 0, s[48:49]
	s_mov_b32 m0, s96
	s_nop 0
	global_load_lds_dwordx4 v[208:209], off
	v_lshl_add_u64 v[208:209], v[220:221], 0, s[48:49]
	s_mov_b32 m0, s97
	s_nop 0
	global_load_lds_dwordx4 v[208:209], off
	s_waitcnt vmcnt(8)
	s_waitcnt lgkmcnt(0)
	s_barrier
	s_setprio 1
	s_waitcnt lgkmcnt(0)
	v_mfma_f32_16x16x32_bf16 v[114:117], v[144:147], v[176:179], v[114:117]
	v_mfma_f32_16x16x32_bf16 v[82:85], v[152:155], v[176:179], v[82:85]
	v_mfma_f32_16x16x32_bf16 v[110:113], v[144:147], v[184:187], v[110:113]
	v_mfma_f32_16x16x32_bf16 v[78:81], v[152:155], v[184:187], v[78:81]
	v_mfma_f32_16x16x32_bf16 v[106:109], v[144:147], v[192:195], v[106:109]
	v_mfma_f32_16x16x32_bf16 v[74:77], v[152:155], v[192:195], v[74:77]
	v_mfma_f32_16x16x32_bf16 v[98:101], v[144:147], v[200:203], v[98:101]
	v_mfma_f32_16x16x32_bf16 v[70:73], v[152:155], v[200:203], v[70:73]
	v_mfma_f32_16x16x32_bf16 v[114:117], v[148:151], v[180:183], v[114:117]
	v_mfma_f32_16x16x32_bf16 v[82:85], v[156:159], v[180:183], v[82:85]
	v_mfma_f32_16x16x32_bf16 v[110:113], v[148:151], v[188:191], v[110:113]
	v_mfma_f32_16x16x32_bf16 v[78:81], v[156:159], v[188:191], v[78:81]
	v_mfma_f32_16x16x32_bf16 v[106:109], v[148:151], v[196:199], v[106:109]
	v_mfma_f32_16x16x32_bf16 v[74:77], v[156:159], v[196:199], v[74:77]
	v_mfma_f32_16x16x32_bf16 v[98:101], v[148:151], v[204:207], v[98:101]
	v_mfma_f32_16x16x32_bf16 v[70:73], v[156:159], v[204:207], v[70:73]
	v_mfma_f32_16x16x32_bf16 v[50:53], v[160:163], v[176:179], v[50:53]
	v_mfma_f32_16x16x32_bf16 v[18:21], v[168:171], v[176:179], v[18:21]
	v_mfma_f32_16x16x32_bf16 v[46:49], v[160:163], v[184:187], v[46:49]
	v_mfma_f32_16x16x32_bf16 v[10:13], v[168:171], v[184:187], v[10:13]
	v_mfma_f32_16x16x32_bf16 v[42:45], v[160:163], v[192:195], v[42:45]
	v_mfma_f32_16x16x32_bf16 v[6:9], v[168:171], v[192:195], v[6:9]
	v_mfma_f32_16x16x32_bf16 v[34:37], v[160:163], v[200:203], v[34:37]
	v_mfma_f32_16x16x32_bf16 v[2:5], v[168:171], v[200:203], v[2:5]
	v_mfma_f32_16x16x32_bf16 v[50:53], v[164:167], v[180:183], v[50:53]
	v_mfma_f32_16x16x32_bf16 v[18:21], v[172:175], v[180:183], v[18:21]
	v_mfma_f32_16x16x32_bf16 v[46:49], v[164:167], v[188:191], v[46:49]
	v_mfma_f32_16x16x32_bf16 v[10:13], v[172:175], v[188:191], v[10:13]
	v_mfma_f32_16x16x32_bf16 v[42:45], v[164:167], v[196:199], v[42:45]
	v_mfma_f32_16x16x32_bf16 v[6:9], v[172:175], v[196:199], v[6:9]
	v_mfma_f32_16x16x32_bf16 v[34:37], v[164:167], v[204:207], v[34:37]
	v_mfma_f32_16x16x32_bf16 v[2:5], v[172:175], v[204:207], v[2:5]
	s_setprio 0
	s_barrier
	s_add_i32 vcc_hi, vcc_hi, 2
	s_add_u32 s54, s54, 0x100
	s_addc_u32 vcc_lo, vcc_lo, 0
	s_cmp_gt_u32 vcc_hi, 29
	s_mov_b64 s[18:19], s[8:9]
	s_cbranch_scc0 .LBB0_314
	s_and_b64 vcc, exec, s[12:13]
	s_cbranch_vccz .LBB0_317
	s_barrier

; #define PG8_STAGE(bufoff, gbase, voff) do { _Pragma("unroll") for (int _i = 0; _i < 2; ++_i) \
;         __builtin_amdgcn_global_load_lds((const unsigned*)((const char*)(gbase) + (voff)[_i]), (PG8_LAS unsigned*)(lds + (bufoff) + ldsw + _i * 8192), 16, 0, 0); } while (0)
; #define PG8_LDA(dst, b, h) do { _Pragma("unroll") for (int m = 0; m < 4; ++m) _Pragma("unroll") for (int k = 0; k < 2; ++k) dst[m][k] = *(const PG8_LAS bf16x8*)(lds + PG8_SA(b, h) + aoff + m * 2048 + k * 1024); } while (0)
; #define PG8_LDB(dst, b, h) do { _Pragma("unroll") for (int n = 0; n < 2; ++n) _Pragma("unroll") for (int k = 0; k < 2; ++k) dst[n][k] = *(const PG8_LAS bf16x8*)(lds + PG8_SB(b, h) + boff + n * 2048 + k * 1024); } while (0)
; #define PG8_MMA(ai, bj, At, Bt) do { __builtin_amdgcn_s_setprio(1); _Pragma("unroll") for (int m = 0; m < 4; ++m) _Pragma("unroll") for (int n = 0; n < 2; ++n) _Pragma("unroll") for (int k = 0; k < 2; ++k) \
;         acc[ai][bj][m][n] = __builtin_amdgcn_mfma_f32_16x16x32_bf16(Bt[n][k], At[m][k], acc[ai][bj][m][n], 0, 0, 0); __builtin_amdgcn_s_setprio(0); } while (0)
; #define PG8_WAIT_V(n) asm volatile("s_waitcnt vmcnt(" #n ")" ::: "memory")
; #define PG8_BAR __builtin_amdgcn_s_barrier()
; template <class Epi, class Sched, bool ALIGN_EPI = false, bool SP2 = false>
; __device__ __forceinline__ void gemm_phase(PG8_LAS unsigned char* lds, const Gemm g, const Sched& S, const Epi& E) {
;     ...
;         for (int t = 0; t < nt; t += 2) {
;             const bool last = (t == nt - 2);
;             const char* a1 = cA + (size_t)(t + 1) * kstep;
;             const char* a2 = last ? nA : cA + (size_t)(t + 2) * kstep; const char* b2 = last ? nB : cB + (size_t)(t + 2) * kstep;
;             const char* a3 = a2 + kstep; const char* b3 = b2 + kstep;
;             if (last && has_next) S.a_ready(nxt);
;             if constexpr (SP2) {
;             PG8_LDB(B0, 0, 0); PG8_LDB(B1, 0, 1); PG8_SCHED; PG8_LDA(At, 0, 0); PG8_STAGE(PG8_SA(1, 1), a1 + hstep, voffA);
;             PG8_WAIT_V(8); PG8_WAIT_L(0); PG8_BAR; PG8_MMA(0, 0, At, B0); PG8_MMA(0, 1, At, B1); PG8_BAR; PG8_SCHED;
;             PG8_LDA(At, 0, 1); PG8_STAGE(PG8_SB(0, 0), b2, voffB); PG8_STAGE(PG8_SB(0, 1), b2 + hstep, voffB); PG8_STAGE(PG8_SA(0, 0), a2, voffA);
;             PG8_WAIT_V(8); PG8_WAIT_L(0); PG8_BAR; PG8_MMA(1, 0, At, B0); PG8_MMA(1, 1, At, B1); PG8_BAR; PG8_SCHED;
.LBB0_380:
	s_add_i32 s38, s4, 2
	s_add_u32 s39, s36, 0x80
	s_addc_u32 s5, s37, 0
	s_add_i32 vcc_lo, 0, 0x10000
	s_cmp_eq_u32 s90, s4
	s_cselect_b32 s5, s9, s5
	s_cselect_b32 s4, s8, s39
	s_cselect_b32 s97, s19, s95
	s_cselect_b32 s96, s18, s94
	s_add_i32 s39, 0, 0x14000
	v_add_u32_e32 v156, vcc_lo, v1
	v_add_u32_e32 v172, s39, v1
	ds_read_b128 v[144:147], v156
	ds_read_b128 v[148:151], v156 offset:1024
	ds_read_b128 v[152:155], v156 offset:2048
	ds_read_b128 v[156:159], v156 offset:3072
	ds_read_b128 v[160:163], v172
	ds_read_b128 v[164:167], v172 offset:1024
	ds_read_b128 v[168:171], v172 offset:2048
	ds_read_b128 v[172:175], v172 offset:3072
	v_lshl_add_u64 v[208:209], s[36:37], 0, v[142:143]
	s_add_i32 m0, s41, 0xc000
	ds_read_b128 v[176:179], v17
	ds_read_b128 v[180:183], v17 offset:1024
	ds_read_b128 v[184:187], v17 offset:2048
	ds_read_b128 v[188:191], v17 offset:3072
	ds_read_b128 v[192:195], v17 offset:4096
	ds_read_b128 v[196:199], v17 offset:5120
	ds_read_b128 v[200:203], v17 offset:6144
	ds_read_b128 v[204:207], v17 offset:7168
	global_load_lds_dwordx4 v[208:209], off
	v_lshl_add_u64 v[208:209], s[36:37], 0, v[140:141]
	s_add_i32 m0, s41, 0xe000
	s_nop 0
	global_load_lds_dwordx4 v[208:209], off
	s_waitcnt vmcnt(8)
	s_waitcnt lgkmcnt(0)
	s_barrier
	s_setprio 1
	s_waitcnt lgkmcnt(0)
	v_mfma_f32_16x16x32_bf16 v[130:133], v[144:147], v[176:179], v[130:133]
	v_mfma_f32_16x16x32_bf16 v[126:129], v[152:155], v[176:179], v[126:129]
	v_mfma_f32_16x16x32_bf16 v[122:125], v[144:147], v[184:187], v[122:125]
	v_mfma_f32_16x16x32_bf16 v[114:117], v[152:155], v[184:187], v[114:117]
	v_mfma_f32_16x16x32_bf16 v[106:109], v[144:147], v[192:195], v[106:109]
	v_mfma_f32_16x16x32_bf16 v[98:101], v[152:155], v[192:195], v[98:101]
	v_mfma_f32_16x16x32_bf16 v[90:93], v[144:147], v[200:203], v[90:93]
	v_mfma_f32_16x16x32_bf16 v[82:85], v[152:155], v[200:203], v[82:85]
	v_mfma_f32_16x16x32_bf16 v[130:133], v[148:151], v[180:183], v[130:133]
	v_mfma_f32_16x16x32_bf16 v[126:129], v[156:159], v[180:183], v[126:129]
	v_mfma_f32_16x16x32_bf16 v[122:125], v[148:151], v[188:191], v[122:125]
	v_mfma_f32_16x16x32_bf16 v[114:117], v[156:159], v[188:191], v[114:117]
	v_mfma_f32_16x16x32_bf16 v[106:109], v[148:151], v[196:199], v[106:109]
	v_mfma_f32_16x16x32_bf16 v[98:101], v[156:159], v[196:199], v[98:101]
	v_mfma_f32_16x16x32_bf16 v[90:93], v[148:151], v[204:207], v[90:93]
	v_mfma_f32_16x16x32_bf16 v[82:85], v[156:159], v[204:207], v[82:85]
	v_mfma_f32_16x16x32_bf16 v[118:121], v[160:163], v[176:179], v[118:121]
	v_mfma_f32_16x16x32_bf16 v[110:113], v[168:171], v[176:179], v[110:113]
	v_mfma_f32_16x16x32_bf16 v[102:105], v[160:163], v[184:187], v[102:105]
	v_mfma_f32_16x16x32_bf16 v[94:97], v[168:171], v[184:187], v[94:97]
	v_mfma_f32_16x16x32_bf16 v[86:89], v[160:163], v[192:195], v[86:89]
	v_mfma_f32_16x16x32_bf16 v[78:81], v[168:171], v[192:195], v[78:81]
	v_mfma_f32_16x16x32_bf16 v[74:77], v[160:163], v[200:203], v[74:77]
	v_mfma_f32_16x16x32_bf16 v[70:73], v[168:171], v[200:203], v[70:73]
	v_mfma_f32_16x16x32_bf16 v[118:121], v[164:167], v[180:183], v[118:121]
	v_mfma_f32_16x16x32_bf16 v[110:113], v[172:175], v[180:183], v[110:113]
	v_mfma_f32_16x16x32_bf16 v[102:105], v[164:167], v[188:191], v[102:105]
	v_mfma_f32_16x16x32_bf16 v[94:97], v[172:175], v[188:191], v[94:97]
	v_mfma_f32_16x16x32_bf16 v[86:89], v[164:167], v[196:199], v[86:89]
	v_mfma_f32_16x16x32_bf16 v[78:81], v[172:175], v[196:199], v[78:81]
	v_mfma_f32_16x16x32_bf16 v[74:77], v[164:167], v[204:207], v[74:77]
	v_mfma_f32_16x16x32_bf16 v[70:73], v[172:175], v[204:207], v[70:73]
	s_setprio 0
	s_barrier
	s_add_i32 vcc_lo, vcc_lo, s64
	v_lshl_add_u64 v[208:209], s[96:97], 0, v[136:137]
	s_mov_b32 m0, vcc_lo
	ds_read_b128 v[176:179], v17 offset:16384
	ds_read_b128 v[180:183], v17 offset:17408
	ds_read_b128 v[184:187], v17 offset:18432
	ds_read_b128 v[188:191], v17 offset:19456
	ds_read_b128 v[192:195], v17 offset:20480
	ds_read_b128 v[196:199], v17 offset:21504
	ds_read_b128 v[200:203], v17 offset:22528
	ds_read_b128 v[204:207], v17 offset:23552
	global_load_lds_dwordx4 v[208:209], off
	s_add_i32 m0, vcc_lo, 0x2000
	v_lshl_add_u64 v[214:215], s[96:97], 0, v[14:15]
	s_add_u32 s96, s96, s54
	s_addc_u32 s97, s97, 0
	s_add_i32 s39, s39, s64
	global_load_lds_dwordx4 v[214:215], off
	v_lshl_add_u64 v[216:217], s[96:97], 0, v[136:137]
	s_mov_b32 m0, s39
	v_lshl_add_u64 v[220:221], s[96:97], 0, v[14:15]
	global_load_lds_dwordx4 v[216:217], off
	s_add_i32 m0, s39, 0x2000
	v_lshl_add_u64 v[222:223], s[4:5], 0, v[138:139]
	global_load_lds_dwordx4 v[220:221], off
	s_mov_b32 m0, s41
	v_lshl_add_u64 v[232:233], s[4:5], 0, v[134:135]
	global_load_lds_dwordx4 v[222:223], off
	s_mov_b32 m0, s43
	s_nop 0
	global_load_lds_dwordx4 v[232:233], off
	s_waitcnt vmcnt(8)
	s_waitcnt lgkmcnt(0)
	s_barrier
; #define PG8_STAGE(bufoff, gbase, voff) do { _Pragma("unroll") for (int _i = 0; _i < 2; ++_i) \
;         __builtin_amdgcn_global_load_lds((const unsigned*)((const char*)(gbase) + (voff)[_i]), (PG8_LAS unsigned*)(lds + (bufoff) + ldsw + _i * 8192), 16, 0, 0); } while (0)
; #define PG8_LDA(dst, b, h) do { _Pragma("unroll") for (int m = 0; m < 4; ++m) _Pragma("unroll") for (int k = 0; k < 2; ++k) dst[m][k] = *(const PG8_LAS bf16x8*)(lds + PG8_SA(b, h) + aoff + m * 2048 + k * 1024); } while (0)
; #define PG8_LDB(dst, b, h) do { _Pragma("unroll") for (int n = 0; n < 2; ++n) _Pragma("unroll") for (int k = 0; k < 2; ++k) dst[n][k] = *(const PG8_LAS bf16x8*)(lds + PG8_SB(b, h) + boff + n * 2048 + k * 1024); } while (0)
; #define PG8_MMA(ai, bj, At, Bt) do { __builtin_amdgcn_s_setprio(1); _Pragma("unroll") for (int m = 0; m < 4; ++m) _Pragma("unroll") for (int n = 0; n < 2; ++n) _Pragma("unroll") for (int k = 0; k < 2; ++k) \
;         acc[ai][bj][m][n] = __builtin_amdgcn_mfma_f32_16x16x32_bf16(Bt[n][k], At[m][k], acc[ai][bj][m][n], 0, 0, 0); __builtin_amdgcn_s_setprio(0); } while (0)
; #define PG8_WAIT_V(n) asm volatile("s_waitcnt vmcnt(" #n ")" ::: "memory")
; #define PG8_WAIT_L(n) asm volatile("s_waitcnt lgkmcnt(" #n ")" ::: "memory")
; #define PG8_BAR __builtin_amdgcn_s_barrier()
; #define PG8_SCHED __builtin_amdgcn_sched_barrier(0)
; template <class Epi, class Sched, bool ALIGN_EPI = false, bool SP2 = false>
; __device__ __forceinline__ void gemm_phase(PG8_LAS unsigned char* lds, const Gemm g, const Sched& S, const Epi& E) {
;     ...
;             PG8_WAIT_V(8); PG8_WAIT_L(0); PG8_BAR; PG8_MMA(1, 0, At, B0); PG8_MMA(1, 1, At, B1); PG8_BAR; PG8_SCHED;
;             PG8_LDB(B0, 1, 0); PG8_LDB(B1, 1, 1); PG8_SCHED; PG8_LDA(At, 1, 0); PG8_STAGE(PG8_SA(0, 1), a2 + hstep, voffA);
;             PG8_WAIT_V(8); PG8_WAIT_L(0); PG8_BAR; PG8_MMA(0, 0, At, B0); PG8_MMA(0, 1, At, B1); PG8_BAR; PG8_SCHED;
	s_setprio 1
	s_waitcnt lgkmcnt(0)
	v_mfma_f32_16x16x32_bf16 v[66:69], v[144:147], v[176:179], v[66:69]
	v_mfma_f32_16x16x32_bf16 v[62:65], v[152:155], v[176:179], v[62:65]
	v_mfma_f32_16x16x32_bf16 v[58:61], v[144:147], v[184:187], v[58:61]
	v_mfma_f32_16x16x32_bf16 v[50:53], v[152:155], v[184:187], v[50:53]
	v_mfma_f32_16x16x32_bf16 v[42:45], v[144:147], v[192:195], v[42:45]
	v_mfma_f32_16x16x32_bf16 v[34:37], v[152:155], v[192:195], v[34:37]
	v_mfma_f32_16x16x32_bf16 v[26:29], v[144:147], v[200:203], v[26:29]
	v_mfma_f32_16x16x32_bf16 v[18:21], v[152:155], v[200:203], v[18:21]
	v_mfma_f32_16x16x32_bf16 v[66:69], v[148:151], v[180:183], v[66:69]
	v_mfma_f32_16x16x32_bf16 v[62:65], v[156:159], v[180:183], v[62:65]
	v_mfma_f32_16x16x32_bf16 v[58:61], v[148:151], v[188:191], v[58:61]
	v_mfma_f32_16x16x32_bf16 v[50:53], v[156:159], v[188:191], v[50:53]
	v_mfma_f32_16x16x32_bf16 v[42:45], v[148:151], v[196:199], v[42:45]
	v_mfma_f32_16x16x32_bf16 v[34:37], v[156:159], v[196:199], v[34:37]
	v_mfma_f32_16x16x32_bf16 v[26:29], v[148:151], v[204:207], v[26:29]
	v_mfma_f32_16x16x32_bf16 v[18:21], v[156:159], v[204:207], v[18:21]
	v_mfma_f32_16x16x32_bf16 v[54:57], v[160:163], v[176:179], v[54:57]
	v_mfma_f32_16x16x32_bf16 v[46:49], v[168:171], v[176:179], v[46:49]
	v_mfma_f32_16x16x32_bf16 v[38:41], v[160:163], v[184:187], v[38:41]
	v_mfma_f32_16x16x32_bf16 v[30:33], v[168:171], v[184:187], v[30:33]
	v_mfma_f32_16x16x32_bf16 v[22:25], v[160:163], v[192:195], v[22:25]
	v_mfma_f32_16x16x32_bf16 v[10:13], v[168:171], v[192:195], v[10:13]
	v_mfma_f32_16x16x32_bf16 v[6:9], v[160:163], v[200:203], v[6:9]
	v_mfma_f32_16x16x32_bf16 v[2:5], v[168:171], v[200:203], v[2:5]
	v_mfma_f32_16x16x32_bf16 v[54:57], v[164:167], v[180:183], v[54:57]
	v_mfma_f32_16x16x32_bf16 v[46:49], v[172:175], v[180:183], v[46:49]
	v_mfma_f32_16x16x32_bf16 v[38:41], v[164:167], v[188:191], v[38:41]
	v_mfma_f32_16x16x32_bf16 v[30:33], v[172:175], v[188:191], v[30:33]
	v_mfma_f32_16x16x32_bf16 v[22:25], v[164:167], v[196:199], v[22:25]
	v_mfma_f32_16x16x32_bf16 v[10:13], v[172:175], v[196:199], v[10:13]
	v_mfma_f32_16x16x32_bf16 v[6:9], v[164:167], v[204:207], v[6:9]
	v_mfma_f32_16x16x32_bf16 v[2:5], v[172:175], v[204:207], v[2:5]
	s_setprio 0
	s_barrier
	s_add_i32 s39, 0, 0x18000
	s_add_i32 s96, 0, 0x1c000
	v_add_u32_e32 v156, s39, v1
	v_add_u32_e32 v172, s96, v1
	ds_read_b128 v[144:147], v156
	ds_read_b128 v[148:151], v156 offset:1024
	ds_read_b128 v[152:155], v156 offset:2048
	ds_read_b128 v[156:159], v156 offset:3072
	ds_read_b128 v[160:163], v172
	ds_read_b128 v[164:167], v172 offset:1024
	ds_read_b128 v[168:171], v172 offset:2048
	ds_read_b128 v[172:175], v172 offset:3072
	s_add_u32 s4, s4, s54
	s_addc_u32 s5, s5, 0
	s_mov_b32 m0, s65
	v_lshl_add_u64 v[234:235], s[4:5], 0, v[138:139]
	ds_read_b128 v[176:179], v17 offset:32768
	ds_read_b128 v[180:183], v17 offset:33792
	ds_read_b128 v[184:187], v17 offset:34816
	ds_read_b128 v[188:191], v17 offset:35840
	ds_read_b128 v[192:195], v17 offset:36864
	ds_read_b128 v[196:199], v17 offset:37888
	ds_read_b128 v[200:203], v17 offset:38912
	ds_read_b128 v[204:207], v17 offset:39936
	global_load_lds_dwordx4 v[234:235], off
	v_lshl_add_u64 v[234:235], s[4:5], 0, v[134:135]
	s_mov_b32 m0, s68
	s_nop 0
	global_load_lds_dwordx4 v[234:235], off
	s_waitcnt vmcnt(8)
	s_waitcnt lgkmcnt(0)
	s_barrier
	s_setprio 1
	s_waitcnt lgkmcnt(0)
	v_mfma_f32_16x16x32_bf16 v[130:133], v[144:147], v[176:179], v[130:133]
	v_mfma_f32_16x16x32_bf16 v[126:129], v[152:155], v[176:179], v[126:129]
	v_mfma_f32_16x16x32_bf16 v[122:125], v[144:147], v[184:187], v[122:125]
	v_mfma_f32_16x16x32_bf16 v[114:117], v[152:155], v[184:187], v[114:117]
	v_mfma_f32_16x16x32_bf16 v[106:109], v[144:147], v[192:195], v[106:109]
	v_mfma_f32_16x16x32_bf16 v[98:101], v[152:155], v[192:195], v[98:101]
	v_mfma_f32_16x16x32_bf16 v[90:93], v[144:147], v[200:203], v[90:93]
	v_mfma_f32_16x16x32_bf16 v[82:85], v[152:155], v[200:203], v[82:85]
	v_mfma_f32_16x16x32_bf16 v[130:133], v[148:151], v[180:183], v[130:133]
	v_mfma_f32_16x16x32_bf16 v[126:129], v[156:159], v[180:183], v[126:129]
	v_mfma_f32_16x16x32_bf16 v[122:125], v[148:151], v[188:191], v[122:125]
	v_mfma_f32_16x16x32_bf16 v[114:117], v[156:159], v[188:191], v[114:117]
	v_mfma_f32_16x16x32_bf16 v[106:109], v[148:151], v[196:199], v[106:109]
	v_mfma_f32_16x16x32_bf16 v[98:101], v[156:159], v[196:199], v[98:101]
	v_mfma_f32_16x16x32_bf16 v[90:93], v[148:151], v[204:207], v[90:93]
	v_mfma_f32_16x16x32_bf16 v[82:85], v[156:159], v[204:207], v[82:85]
	v_mfma_f32_16x16x32_bf16 v[118:121], v[160:163], v[176:179], v[118:121]
	v_mfma_f32_16x16x32_bf16 v[110:113], v[168:171], v[176:179], v[110:113]
	v_mfma_f32_16x16x32_bf16 v[102:105], v[160:163], v[184:187], v[102:105]
	v_mfma_f32_16x16x32_bf16 v[94:97], v[168:171], v[184:187], v[94:97]
	v_mfma_f32_16x16x32_bf16 v[86:89], v[160:163], v[192:195], v[86:89]
	v_mfma_f32_16x16x32_bf16 v[78:81], v[168:171], v[192:195], v[78:81]
	v_mfma_f32_16x16x32_bf16 v[74:77], v[160:163], v[200:203], v[74:77]
	v_mfma_f32_16x16x32_bf16 v[70:73], v[168:171], v[200:203], v[70:73]
	v_mfma_f32_16x16x32_bf16 v[118:121], v[164:167], v[180:183], v[118:121]
	v_mfma_f32_16x16x32_bf16 v[110:113], v[172:175], v[180:183], v[110:113]
	v_mfma_f32_16x16x32_bf16 v[102:105], v[164:167], v[188:191], v[102:105]
	v_mfma_f32_16x16x32_bf16 v[94:97], v[172:175], v[188:191], v[94:97]
	v_mfma_f32_16x16x32_bf16 v[86:89], v[164:167], v[196:199], v[86:89]
	v_mfma_f32_16x16x32_bf16 v[78:81], v[172:175], v[196:199], v[78:81]
	v_mfma_f32_16x16x32_bf16 v[74:77], v[164:167], v[204:207], v[74:77]
	v_mfma_f32_16x16x32_bf16 v[70:73], v[172:175], v[204:207], v[70:73]
	s_setprio 0
	s_barrier
; #define PG8_STAGE(bufoff, gbase, voff) do { _Pragma("unroll") for (int _i = 0; _i < 2; ++_i) \
;         __builtin_amdgcn_global_load_lds((const unsigned*)((const char*)(gbase) + (voff)[_i]), (PG8_LAS unsigned*)(lds + (bufoff) + ldsw + _i * 8192), 16, 0, 0); } while (0)
; #define PG8_LDA(dst, b, h) do { _Pragma("unroll") for (int m = 0; m < 4; ++m) _Pragma("unroll") for (int k = 0; k < 2; ++k) dst[m][k] = *(const PG8_LAS bf16x8*)(lds + PG8_SA(b, h) + aoff + m * 2048 + k * 1024); } while (0)
; #define PG8_MMA(ai, bj, At, Bt) do { __builtin_amdgcn_s_setprio(1); _Pragma("unroll") for (int m = 0; m < 4; ++m) _Pragma("unroll") for (int n = 0; n < 2; ++n) _Pragma("unroll") for (int k = 0; k < 2; ++k) \
;         acc[ai][bj][m][n] = __builtin_amdgcn_mfma_f32_16x16x32_bf16(Bt[n][k], At[m][k], acc[ai][bj][m][n], 0, 0, 0); __builtin_amdgcn_s_setprio(0); } while (0)
; #define PG8_WAIT_V(n) asm volatile("s_waitcnt vmcnt(" #n ")" ::: "memory")
; #define PG8_WAIT_L(n) asm volatile("s_waitcnt lgkmcnt(" #n ")" ::: "memory")
; #define PG8_BAR __builtin_amdgcn_s_barrier()
; #define PG8_SCHED __builtin_amdgcn_sched_barrier(0)
; template <class Epi, class Sched, bool ALIGN_EPI = false, bool SP2 = false>
; __device__ __forceinline__ void gemm_phase(PG8_LAS unsigned char* lds, const Gemm g, const Sched& S, const Epi& E) {
;     ...
;             PG8_LDA(At, 1, 1); PG8_STAGE(PG8_SB(1, 0), b3, voffB); PG8_STAGE(PG8_SB(1, 1), b3 + hstep, voffB); PG8_STAGE(PG8_SA(1, 0), a3, voffA);
;             PG8_WAIT_V(8); PG8_WAIT_L(0); PG8_BAR; PG8_MMA(1, 0, At, B0); PG8_MMA(1, 1, At, B1); PG8_BAR; PG8_SCHED;
;     ...
;         if constexpr (ALIGN_EPI) { if (wr == 0) PG8_BAR; }
	s_add_i32 s4, s39, s64
	v_lshl_add_u64 v[208:209], v[208:209], 0, s[48:49]
	s_mov_b32 m0, s4
	ds_read_b128 v[176:179], v17 offset:49152
	ds_read_b128 v[180:183], v17 offset:50176
	ds_read_b128 v[184:187], v17 offset:51200
	ds_read_b128 v[188:191], v17 offset:52224
	ds_read_b128 v[192:195], v17 offset:53248
	ds_read_b128 v[196:199], v17 offset:54272
	ds_read_b128 v[200:203], v17 offset:55296
	ds_read_b128 v[204:207], v17 offset:56320
	global_load_lds_dwordx4 v[208:209], off
	v_lshl_add_u64 v[208:209], v[214:215], 0, s[48:49]
	s_add_i32 m0, s4, 0x2000
	s_add_i32 s4, s96, s64
	global_load_lds_dwordx4 v[208:209], off
	v_lshl_add_u64 v[208:209], v[216:217], 0, s[48:49]
	s_mov_b32 m0, s4
	s_nop 0
	global_load_lds_dwordx4 v[208:209], off
	v_lshl_add_u64 v[208:209], v[220:221], 0, s[48:49]
	s_add_i32 m0, s4, 0x2000
	s_nop 0
	global_load_lds_dwordx4 v[208:209], off
	v_lshl_add_u64 v[208:209], v[222:223], 0, s[48:49]
	s_mov_b32 m0, s88
	s_nop 0
	global_load_lds_dwordx4 v[208:209], off
	v_lshl_add_u64 v[208:209], v[232:233], 0, s[48:49]
	s_mov_b32 m0, s89
	s_nop 0
	global_load_lds_dwordx4 v[208:209], off
	s_waitcnt vmcnt(8)
	s_waitcnt lgkmcnt(0)
	s_barrier
	s_setprio 1
	s_waitcnt lgkmcnt(0)
	v_mfma_f32_16x16x32_bf16 v[66:69], v[144:147], v[176:179], v[66:69]
	v_mfma_f32_16x16x32_bf16 v[62:65], v[152:155], v[176:179], v[62:65]
	v_mfma_f32_16x16x32_bf16 v[58:61], v[144:147], v[184:187], v[58:61]
	v_mfma_f32_16x16x32_bf16 v[50:53], v[152:155], v[184:187], v[50:53]
	v_mfma_f32_16x16x32_bf16 v[42:45], v[144:147], v[192:195], v[42:45]
	v_mfma_f32_16x16x32_bf16 v[34:37], v[152:155], v[192:195], v[34:37]
	v_mfma_f32_16x16x32_bf16 v[26:29], v[144:147], v[200:203], v[26:29]
	v_mfma_f32_16x16x32_bf16 v[18:21], v[152:155], v[200:203], v[18:21]
	v_mfma_f32_16x16x32_bf16 v[66:69], v[148:151], v[180:183], v[66:69]
	v_mfma_f32_16x16x32_bf16 v[62:65], v[156:159], v[180:183], v[62:65]
	v_mfma_f32_16x16x32_bf16 v[58:61], v[148:151], v[188:191], v[58:61]
	v_mfma_f32_16x16x32_bf16 v[50:53], v[156:159], v[188:191], v[50:53]
	v_mfma_f32_16x16x32_bf16 v[42:45], v[148:151], v[196:199], v[42:45]
	v_mfma_f32_16x16x32_bf16 v[34:37], v[156:159], v[196:199], v[34:37]
	v_mfma_f32_16x16x32_bf16 v[26:29], v[148:151], v[204:207], v[26:29]
	v_mfma_f32_16x16x32_bf16 v[18:21], v[156:159], v[204:207], v[18:21]
	v_mfma_f32_16x16x32_bf16 v[54:57], v[160:163], v[176:179], v[54:57]
	v_mfma_f32_16x16x32_bf16 v[46:49], v[168:171], v[176:179], v[46:49]
	v_mfma_f32_16x16x32_bf16 v[38:41], v[160:163], v[184:187], v[38:41]
	v_mfma_f32_16x16x32_bf16 v[30:33], v[168:171], v[184:187], v[30:33]
	v_mfma_f32_16x16x32_bf16 v[22:25], v[160:163], v[192:195], v[22:25]
	v_mfma_f32_16x16x32_bf16 v[10:13], v[168:171], v[192:195], v[10:13]
	v_mfma_f32_16x16x32_bf16 v[6:9], v[160:163], v[200:203], v[6:9]
	v_mfma_f32_16x16x32_bf16 v[2:5], v[168:171], v[200:203], v[2:5]
	v_mfma_f32_16x16x32_bf16 v[54:57], v[164:167], v[180:183], v[54:57]
	v_mfma_f32_16x16x32_bf16 v[46:49], v[172:175], v[180:183], v[46:49]
	v_mfma_f32_16x16x32_bf16 v[38:41], v[164:167], v[188:191], v[38:41]
	v_mfma_f32_16x16x32_bf16 v[30:33], v[172:175], v[188:191], v[30:33]
	v_mfma_f32_16x16x32_bf16 v[22:25], v[164:167], v[196:199], v[22:25]
	v_mfma_f32_16x16x32_bf16 v[10:13], v[172:175], v[196:199], v[10:13]
	v_mfma_f32_16x16x32_bf16 v[6:9], v[164:167], v[204:207], v[6:9]
	v_mfma_f32_16x16x32_bf16 v[2:5], v[172:175], v[204:207], v[2:5]
	s_setprio 0
	s_barrier
	s_add_u32 s94, s94, 0x100
	s_addc_u32 s95, s95, 0
	s_add_u32 s36, s36, 0x100
	s_addc_u32 s37, s37, 0
	s_cmp_ge_u32 s38, s77
	s_mov_b32 s4, s38
	s_cbranch_scc0 .LBB0_380
	s_and_b64 vcc, exec, s[16:17]
	s_cbranch_vccz .LBB0_383
	s_barrier

; #define PG8_STAGE(bufoff, gbase, voff) do { _Pragma("unroll") for (int _i = 0; _i < 2; ++_i) \
;         __builtin_amdgcn_global_load_lds((const unsigned*)((const char*)(gbase) + (voff)[_i]), (PG8_LAS unsigned*)(lds + (bufoff) + ldsw + _i * 8192), 16, 0, 0); } while (0)
; #define PG8_LDA(dst, b, h) do { _Pragma("unroll") for (int m = 0; m < 4; ++m) _Pragma("unroll") for (int k = 0; k < 2; ++k) dst[m][k] = *(const PG8_LAS bf16x8*)(lds + PG8_SA(b, h) + aoff + m * 2048 + k * 1024); } while (0)
; #define PG8_LDB(dst, b, h) do { _Pragma("unroll") for (int n = 0; n < 2; ++n) _Pragma("unroll") for (int k = 0; k < 2; ++k) dst[n][k] = *(const PG8_LAS bf16x8*)(lds + PG8_SB(b, h) + boff + n * 2048 + k * 1024); } while (0)
; #define PG8_MMA(ai, bj, At, Bt) do { __builtin_amdgcn_s_setprio(1); _Pragma("unroll") for (int m = 0; m < 4; ++m) _Pragma("unroll") for (int n = 0; n < 2; ++n) _Pragma("unroll") for (int k = 0; k < 2; ++k) \
;         acc[ai][bj][m][n] = __builtin_amdgcn_mfma_f32_16x16x32_bf16(Bt[n][k], At[m][k], acc[ai][bj][m][n], 0, 0, 0); __builtin_amdgcn_s_setprio(0); } while (0)
; #define PG8_WAIT_V(n) asm volatile("s_waitcnt vmcnt(" #n ")" ::: "memory")
; #define PG8_WAIT_L(n) asm volatile("s_waitcnt lgkmcnt(" #n ")" ::: "memory")
; #define PG8_BAR __builtin_amdgcn_s_barrier()
; template <class Epi, class Sched, bool ALIGN_EPI = false, bool SP2 = false>
; __device__ __forceinline__ void gemm_phase(PG8_LAS unsigned char* lds, const Gemm g, const Sched& S, const Epi& E) {
;     ...
;             const char* a1 = cA + (size_t)(t + 1) * kstep;
;             const char* a2 = last ? nA : cA + (size_t)(t + 2) * kstep; const char* b2 = last ? nB : cB + (size_t)(t + 2) * kstep;
;             const char* a3 = a2 + kstep; const char* b3 = b2 + kstep;
;             if (last && has_next) S.a_ready(nxt);
;             if constexpr (SP2) {
;             PG8_LDB(B0, 0, 0); PG8_LDB(B1, 0, 1); PG8_SCHED; PG8_LDA(At, 0, 0); PG8_STAGE(PG8_SA(1, 1), a1 + hstep, voffA);
;             PG8_WAIT_V(8); PG8_WAIT_L(0); PG8_BAR; PG8_MMA(0, 0, At, B0); PG8_MMA(0, 1, At, B1); PG8_BAR; PG8_SCHED;
;             PG8_LDA(At, 0, 1); PG8_STAGE(PG8_SB(0, 0), b2, voffB); PG8_STAGE(PG8_SB(0, 1), b2 + hstep, voffB); PG8_STAGE(PG8_SA(0, 0), a2, voffA);
;             PG8_WAIT_V(8); PG8_WAIT_L(0); PG8_BAR; PG8_MMA(1, 0, At, B0); PG8_MMA(1, 1, At, B1); PG8_BAR; PG8_SCHED;
.LBB0_402:
	s_add_u32 s36, s18, 0x100
	s_addc_u32 s37, s19, 0
	s_add_i32 s47, 0, 0x10000
	s_cmp_eq_u32 s43, 28
	s_cselect_b32 s39, s9, s37
	s_cselect_b32 s38, s8, s36
	s_cselect_b32 s5, s17, s41
	s_cselect_b32 s4, s16, s31
	s_add_i32 s92, 0, 0x14000
	v_add_u32_e32 v156, s47, v1
	v_add_u32_e32 v172, s92, v1
	ds_read_b128 v[144:147], v156
	ds_read_b128 v[148:151], v156 offset:1024
	ds_read_b128 v[152:155], v156 offset:2048
	ds_read_b128 v[156:159], v156 offset:3072
	ds_read_b128 v[160:163], v172
	ds_read_b128 v[164:167], v172 offset:1024
	ds_read_b128 v[168:171], v172 offset:2048
	ds_read_b128 v[172:175], v172 offset:3072
	s_add_i32 m0, s54, 0xc000
	ds_read_b128 v[176:179], v17
	ds_read_b128 v[180:183], v17 offset:1024
	ds_read_b128 v[184:187], v17 offset:2048
	ds_read_b128 v[188:191], v17 offset:3072
	ds_read_b128 v[192:195], v17 offset:4096
	ds_read_b128 v[196:199], v17 offset:5120
	ds_read_b128 v[200:203], v17 offset:6144
	ds_read_b128 v[204:207], v17 offset:7168
	global_load_lds_dwordx4 v142, s[18:19]
	s_add_i32 m0, s54, 0xe000
	s_nop 0
	global_load_lds_dwordx4 v140, s[18:19]
	s_waitcnt vmcnt(8)
	s_waitcnt lgkmcnt(0)
	s_barrier
	s_setprio 1
	s_waitcnt lgkmcnt(0)
	v_mfma_f32_16x16x32_bf16 v[130:133], v[144:147], v[176:179], v[130:133]
	v_mfma_f32_16x16x32_bf16 v[122:125], v[152:155], v[176:179], v[122:125]
	v_mfma_f32_16x16x32_bf16 v[114:117], v[144:147], v[184:187], v[114:117]
	v_mfma_f32_16x16x32_bf16 v[106:109], v[152:155], v[184:187], v[106:109]
	v_mfma_f32_16x16x32_bf16 v[98:101], v[144:147], v[192:195], v[98:101]
	v_mfma_f32_16x16x32_bf16 v[90:93], v[152:155], v[192:195], v[90:93]
	v_mfma_f32_16x16x32_bf16 v[82:85], v[144:147], v[200:203], v[82:85]
	v_mfma_f32_16x16x32_bf16 v[74:77], v[152:155], v[200:203], v[74:77]
	v_mfma_f32_16x16x32_bf16 v[130:133], v[148:151], v[180:183], v[130:133]
	v_mfma_f32_16x16x32_bf16 v[122:125], v[156:159], v[180:183], v[122:125]
	v_mfma_f32_16x16x32_bf16 v[114:117], v[148:151], v[188:191], v[114:117]
	v_mfma_f32_16x16x32_bf16 v[106:109], v[156:159], v[188:191], v[106:109]
	v_mfma_f32_16x16x32_bf16 v[98:101], v[148:151], v[196:199], v[98:101]
	v_mfma_f32_16x16x32_bf16 v[90:93], v[156:159], v[196:199], v[90:93]
	v_mfma_f32_16x16x32_bf16 v[82:85], v[148:151], v[204:207], v[82:85]
	v_mfma_f32_16x16x32_bf16 v[74:77], v[156:159], v[204:207], v[74:77]
	v_mfma_f32_16x16x32_bf16 v[126:129], v[160:163], v[176:179], v[126:129]
	v_mfma_f32_16x16x32_bf16 v[118:121], v[168:171], v[176:179], v[118:121]
	v_mfma_f32_16x16x32_bf16 v[110:113], v[160:163], v[184:187], v[110:113]
	v_mfma_f32_16x16x32_bf16 v[102:105], v[168:171], v[184:187], v[102:105]
	v_mfma_f32_16x16x32_bf16 v[94:97], v[160:163], v[192:195], v[94:97]
	v_mfma_f32_16x16x32_bf16 v[86:89], v[168:171], v[192:195], v[86:89]
	v_mfma_f32_16x16x32_bf16 v[78:81], v[160:163], v[200:203], v[78:81]
	v_mfma_f32_16x16x32_bf16 v[70:73], v[168:171], v[200:203], v[70:73]
	v_mfma_f32_16x16x32_bf16 v[126:129], v[164:167], v[180:183], v[126:129]
	v_mfma_f32_16x16x32_bf16 v[118:121], v[172:175], v[180:183], v[118:121]
	v_mfma_f32_16x16x32_bf16 v[110:113], v[164:167], v[188:191], v[110:113]
	v_mfma_f32_16x16x32_bf16 v[102:105], v[172:175], v[188:191], v[102:105]
	v_mfma_f32_16x16x32_bf16 v[94:97], v[164:167], v[196:199], v[94:97]
	v_mfma_f32_16x16x32_bf16 v[86:89], v[172:175], v[196:199], v[86:89]
	v_mfma_f32_16x16x32_bf16 v[78:81], v[164:167], v[204:207], v[78:81]
	v_mfma_f32_16x16x32_bf16 v[70:73], v[172:175], v[204:207], v[70:73]
	s_setprio 0
	s_barrier
	s_add_i32 s18, s47, s46
	s_mov_b32 m0, s18
	ds_read_b128 v[176:179], v17 offset:16384
	ds_read_b128 v[180:183], v17 offset:17408
	ds_read_b128 v[184:187], v17 offset:18432
	ds_read_b128 v[188:191], v17 offset:19456
	ds_read_b128 v[192:195], v17 offset:20480
	ds_read_b128 v[196:199], v17 offset:21504
	ds_read_b128 v[200:203], v17 offset:22528
	ds_read_b128 v[204:207], v17 offset:23552
	global_load_lds_dwordx4 v136, s[4:5]
	s_add_i32 m0, s18, 0x2000
	s_add_u32 s18, s4, 0x84000
	s_addc_u32 s19, s5, 0
	s_add_i32 s47, s92, s46
	global_load_lds_dwordx4 v14, s[4:5]
	s_mov_b32 m0, s47
	s_nop 0
	global_load_lds_dwordx4 v136, s[18:19]
	s_add_i32 m0, s47, 0x2000
	s_nop 0
	global_load_lds_dwordx4 v14, s[18:19]
	s_mov_b32 m0, s54
	s_nop 0
	global_load_lds_dwordx4 v138, s[38:39]
	s_mov_b32 m0, s64
	s_nop 0
	global_load_lds_dwordx4 v134, s[38:39]
	s_waitcnt vmcnt(8)
	s_waitcnt lgkmcnt(0)
	s_barrier
	s_setprio 1
	s_waitcnt lgkmcnt(0)
	v_mfma_f32_16x16x32_bf16 v[66:69], v[144:147], v[176:179], v[66:69]
	v_mfma_f32_16x16x32_bf16 v[58:61], v[152:155], v[176:179], v[58:61]
	v_mfma_f32_16x16x32_bf16 v[50:53], v[144:147], v[184:187], v[50:53]
	v_mfma_f32_16x16x32_bf16 v[42:45], v[152:155], v[184:187], v[42:45]
	v_mfma_f32_16x16x32_bf16 v[34:37], v[144:147], v[192:195], v[34:37]
	v_mfma_f32_16x16x32_bf16 v[26:29], v[152:155], v[192:195], v[26:29]
	v_mfma_f32_16x16x32_bf16 v[18:21], v[144:147], v[200:203], v[18:21]
	v_mfma_f32_16x16x32_bf16 v[6:9], v[152:155], v[200:203], v[6:9]
	v_mfma_f32_16x16x32_bf16 v[66:69], v[148:151], v[180:183], v[66:69]
	v_mfma_f32_16x16x32_bf16 v[58:61], v[156:159], v[180:183], v[58:61]
	v_mfma_f32_16x16x32_bf16 v[50:53], v[148:151], v[188:191], v[50:53]
	v_mfma_f32_16x16x32_bf16 v[42:45], v[156:159], v[188:191], v[42:45]
	v_mfma_f32_16x16x32_bf16 v[34:37], v[148:151], v[196:199], v[34:37]
	v_mfma_f32_16x16x32_bf16 v[26:29], v[156:159], v[196:199], v[26:29]
	v_mfma_f32_16x16x32_bf16 v[18:21], v[148:151], v[204:207], v[18:21]
	v_mfma_f32_16x16x32_bf16 v[6:9], v[156:159], v[204:207], v[6:9]
	v_mfma_f32_16x16x32_bf16 v[62:65], v[160:163], v[176:179], v[62:65]
	v_mfma_f32_16x16x32_bf16 v[54:57], v[168:171], v[176:179], v[54:57]
	v_mfma_f32_16x16x32_bf16 v[46:49], v[160:163], v[184:187], v[46:49]
	v_mfma_f32_16x16x32_bf16 v[38:41], v[168:171], v[184:187], v[38:41]
	v_mfma_f32_16x16x32_bf16 v[30:33], v[160:163], v[192:195], v[30:33]
	v_mfma_f32_16x16x32_bf16 v[22:25], v[168:171], v[192:195], v[22:25]
	v_mfma_f32_16x16x32_bf16 v[10:13], v[160:163], v[200:203], v[10:13]
	v_mfma_f32_16x16x32_bf16 v[2:5], v[168:171], v[200:203], v[2:5]
	v_mfma_f32_16x16x32_bf16 v[62:65], v[164:167], v[180:183], v[62:65]
	v_mfma_f32_16x16x32_bf16 v[54:57], v[172:175], v[180:183], v[54:57]
	v_mfma_f32_16x16x32_bf16 v[46:49], v[164:167], v[188:191], v[46:49]
	v_mfma_f32_16x16x32_bf16 v[38:41], v[172:175], v[188:191], v[38:41]
	v_mfma_f32_16x16x32_bf16 v[30:33], v[164:167], v[196:199], v[30:33]
	v_mfma_f32_16x16x32_bf16 v[22:25], v[172:175], v[196:199], v[22:25]
	v_mfma_f32_16x16x32_bf16 v[10:13], v[164:167], v[204:207], v[10:13]
	v_mfma_f32_16x16x32_bf16 v[2:5], v[172:175], v[204:207], v[2:5]
	s_setprio 0
	s_barrier
; #define PG8_STAGE(bufoff, gbase, voff) do { _Pragma("unroll") for (int _i = 0; _i < 2; ++_i) \
;         __builtin_amdgcn_global_load_lds((const unsigned*)((const char*)(gbase) + (voff)[_i]), (PG8_LAS unsigned*)(lds + (bufoff) + ldsw + _i * 8192), 16, 0, 0); } while (0)
; #define PG8_LDA(dst, b, h) do { _Pragma("unroll") for (int m = 0; m < 4; ++m) _Pragma("unroll") for (int k = 0; k < 2; ++k) dst[m][k] = *(const PG8_LAS bf16x8*)(lds + PG8_SA(b, h) + aoff + m * 2048 + k * 1024); } while (0)
; #define PG8_LDB(dst, b, h) do { _Pragma("unroll") for (int n = 0; n < 2; ++n) _Pragma("unroll") for (int k = 0; k < 2; ++k) dst[n][k] = *(const PG8_LAS bf16x8*)(lds + PG8_SB(b, h) + boff + n * 2048 + k * 1024); } while (0)
; #define PG8_MMA(ai, bj, At, Bt) do { __builtin_amdgcn_s_setprio(1); _Pragma("unroll") for (int m = 0; m < 4; ++m) _Pragma("unroll") for (int n = 0; n < 2; ++n) _Pragma("unroll") for (int k = 0; k < 2; ++k) \
;         acc[ai][bj][m][n] = __builtin_amdgcn_mfma_f32_16x16x32_bf16(Bt[n][k], At[m][k], acc[ai][bj][m][n], 0, 0, 0); __builtin_amdgcn_s_setprio(0); } while (0)
; #define PG8_WAIT_V(n) asm volatile("s_waitcnt vmcnt(" #n ")" ::: "memory")
; #define PG8_WAIT_L(n) asm volatile("s_waitcnt lgkmcnt(" #n ")" ::: "memory")
; #define PG8_BAR __builtin_amdgcn_s_barrier()
; #define PG8_SCHED __builtin_amdgcn_sched_barrier(0)
; template <class Epi, class Sched, bool ALIGN_EPI = false, bool SP2 = false>
; __device__ __forceinline__ void gemm_phase(PG8_LAS unsigned char* lds, const Gemm g, const Sched& S, const Epi& E) {
;     ...
;             PG8_LDB(B0, 1, 0); PG8_LDB(B1, 1, 1); PG8_SCHED; PG8_LDA(At, 1, 0); PG8_STAGE(PG8_SA(0, 1), a2 + hstep, voffA);
;             PG8_WAIT_V(8); PG8_WAIT_L(0); PG8_BAR; PG8_MMA(0, 0, At, B0); PG8_MMA(0, 1, At, B1); PG8_BAR; PG8_SCHED;
;             PG8_LDA(At, 1, 1); PG8_STAGE(PG8_SB(1, 0), b3, voffB); PG8_STAGE(PG8_SB(1, 1), b3 + hstep, voffB); PG8_STAGE(PG8_SA(1, 0), a3, voffA);
;             PG8_WAIT_V(8); PG8_WAIT_L(0); PG8_BAR; PG8_MMA(1, 0, At, B0); PG8_MMA(1, 1, At, B1); PG8_BAR; PG8_SCHED;
;     ...
;         if constexpr (ALIGN_EPI) { if (wr == 0) PG8_BAR; }
	s_add_i32 s47, 0, 0x18000
	s_add_i32 s92, 0, 0x1c000
	v_add_u32_e32 v156, s47, v1
	v_add_u32_e32 v172, s92, v1
	ds_read_b128 v[144:147], v156
	ds_read_b128 v[148:151], v156 offset:1024
	ds_read_b128 v[152:155], v156 offset:2048
	ds_read_b128 v[156:159], v156 offset:3072
	ds_read_b128 v[160:163], v172
	ds_read_b128 v[164:167], v172 offset:1024
	ds_read_b128 v[168:171], v172 offset:2048
	ds_read_b128 v[172:175], v172 offset:3072
	s_add_u32 s18, s38, 0x84000
	s_addc_u32 s19, s39, 0
	s_mov_b32 m0, s65
	ds_read_b128 v[176:179], v17 offset:32768
	ds_read_b128 v[180:183], v17 offset:33792
	ds_read_b128 v[184:187], v17 offset:34816
	ds_read_b128 v[188:191], v17 offset:35840
	ds_read_b128 v[192:195], v17 offset:36864
	ds_read_b128 v[196:199], v17 offset:37888
	ds_read_b128 v[200:203], v17 offset:38912
	ds_read_b128 v[204:207], v17 offset:39936
	global_load_lds_dwordx4 v138, s[18:19]
	s_mov_b32 m0, s68
	s_nop 0
	global_load_lds_dwordx4 v134, s[18:19]
	s_waitcnt vmcnt(8)
	s_waitcnt lgkmcnt(0)
	s_barrier
	s_setprio 1
	s_waitcnt lgkmcnt(0)
	v_mfma_f32_16x16x32_bf16 v[130:133], v[144:147], v[176:179], v[130:133]
	v_mfma_f32_16x16x32_bf16 v[122:125], v[152:155], v[176:179], v[122:125]
	v_mfma_f32_16x16x32_bf16 v[114:117], v[144:147], v[184:187], v[114:117]
	v_mfma_f32_16x16x32_bf16 v[106:109], v[152:155], v[184:187], v[106:109]
	v_mfma_f32_16x16x32_bf16 v[98:101], v[144:147], v[192:195], v[98:101]
	v_mfma_f32_16x16x32_bf16 v[90:93], v[152:155], v[192:195], v[90:93]
	v_mfma_f32_16x16x32_bf16 v[82:85], v[144:147], v[200:203], v[82:85]
	v_mfma_f32_16x16x32_bf16 v[74:77], v[152:155], v[200:203], v[74:77]
	v_mfma_f32_16x16x32_bf16 v[130:133], v[148:151], v[180:183], v[130:133]
	v_mfma_f32_16x16x32_bf16 v[122:125], v[156:159], v[180:183], v[122:125]
	v_mfma_f32_16x16x32_bf16 v[114:117], v[148:151], v[188:191], v[114:117]
	v_mfma_f32_16x16x32_bf16 v[106:109], v[156:159], v[188:191], v[106:109]
	v_mfma_f32_16x16x32_bf16 v[98:101], v[148:151], v[196:199], v[98:101]
	v_mfma_f32_16x16x32_bf16 v[90:93], v[156:159], v[196:199], v[90:93]
	v_mfma_f32_16x16x32_bf16 v[82:85], v[148:151], v[204:207], v[82:85]
	v_mfma_f32_16x16x32_bf16 v[74:77], v[156:159], v[204:207], v[74:77]
	v_mfma_f32_16x16x32_bf16 v[126:129], v[160:163], v[176:179], v[126:129]
	v_mfma_f32_16x16x32_bf16 v[118:121], v[168:171], v[176:179], v[118:121]
	v_mfma_f32_16x16x32_bf16 v[110:113], v[160:163], v[184:187], v[110:113]
	v_mfma_f32_16x16x32_bf16 v[102:105], v[168:171], v[184:187], v[102:105]
	v_mfma_f32_16x16x32_bf16 v[94:97], v[160:163], v[192:195], v[94:97]
	v_mfma_f32_16x16x32_bf16 v[86:89], v[168:171], v[192:195], v[86:89]
	v_mfma_f32_16x16x32_bf16 v[78:81], v[160:163], v[200:203], v[78:81]
	v_mfma_f32_16x16x32_bf16 v[70:73], v[168:171], v[200:203], v[70:73]
	v_mfma_f32_16x16x32_bf16 v[126:129], v[164:167], v[180:183], v[126:129]
	v_mfma_f32_16x16x32_bf16 v[118:121], v[172:175], v[180:183], v[118:121]
	v_mfma_f32_16x16x32_bf16 v[110:113], v[164:167], v[188:191], v[110:113]
	v_mfma_f32_16x16x32_bf16 v[102:105], v[172:175], v[188:191], v[102:105]
	v_mfma_f32_16x16x32_bf16 v[94:97], v[164:167], v[196:199], v[94:97]
	v_mfma_f32_16x16x32_bf16 v[86:89], v[172:175], v[196:199], v[86:89]
	v_mfma_f32_16x16x32_bf16 v[78:81], v[164:167], v[204:207], v[78:81]
	v_mfma_f32_16x16x32_bf16 v[70:73], v[172:175], v[204:207], v[70:73]
	s_setprio 0
	s_barrier
	s_add_i32 s18, s47, s46
	s_add_u32 s4, s4, 0x80
	s_addc_u32 s5, s5, 0
	s_mov_b32 m0, s18
	ds_read_b128 v[176:179], v17 offset:49152
	ds_read_b128 v[180:183], v17 offset:50176
	ds_read_b128 v[184:187], v17 offset:51200
	ds_read_b128 v[188:191], v17 offset:52224
	ds_read_b128 v[192:195], v17 offset:53248
	ds_read_b128 v[196:199], v17 offset:54272
	ds_read_b128 v[200:203], v17 offset:55296
	ds_read_b128 v[204:207], v17 offset:56320
	global_load_lds_dwordx4 v136, s[4:5]
	s_add_i32 m0, s18, 0x2000
	s_add_i32 s18, s92, s46
	global_load_lds_dwordx4 v14, s[4:5]
	s_add_u32 s4, s4, 0x84000
	s_addc_u32 s5, s5, 0
	s_mov_b32 m0, s18
	s_nop 0
	global_load_lds_dwordx4 v136, s[4:5]
	s_add_i32 m0, s18, 0x2000
	s_nop 0
	global_load_lds_dwordx4 v14, s[4:5]
	s_add_i32 m0, s54, 0x7f80
	s_nop 0
	global_load_lds_dwordx4 v138, s[38:39] offset:128
	s_add_i32 m0, s54, 0x9f80
	s_nop 0
	global_load_lds_dwordx4 v134, s[38:39] offset:128
	s_waitcnt vmcnt(8)
	s_waitcnt lgkmcnt(0)
	s_barrier
	s_setprio 1
	s_waitcnt lgkmcnt(0)
	v_mfma_f32_16x16x32_bf16 v[66:69], v[144:147], v[176:179], v[66:69]
	v_mfma_f32_16x16x32_bf16 v[58:61], v[152:155], v[176:179], v[58:61]
	v_mfma_f32_16x16x32_bf16 v[50:53], v[144:147], v[184:187], v[50:53]
	v_mfma_f32_16x16x32_bf16 v[42:45], v[152:155], v[184:187], v[42:45]
	v_mfma_f32_16x16x32_bf16 v[34:37], v[144:147], v[192:195], v[34:37]
	v_mfma_f32_16x16x32_bf16 v[26:29], v[152:155], v[192:195], v[26:29]
	v_mfma_f32_16x16x32_bf16 v[18:21], v[144:147], v[200:203], v[18:21]
	v_mfma_f32_16x16x32_bf16 v[6:9], v[152:155], v[200:203], v[6:9]
	v_mfma_f32_16x16x32_bf16 v[66:69], v[148:151], v[180:183], v[66:69]
	v_mfma_f32_16x16x32_bf16 v[58:61], v[156:159], v[180:183], v[58:61]
	v_mfma_f32_16x16x32_bf16 v[50:53], v[148:151], v[188:191], v[50:53]
	v_mfma_f32_16x16x32_bf16 v[42:45], v[156:159], v[188:191], v[42:45]
	v_mfma_f32_16x16x32_bf16 v[34:37], v[148:151], v[196:199], v[34:37]
	v_mfma_f32_16x16x32_bf16 v[26:29], v[156:159], v[196:199], v[26:29]
	v_mfma_f32_16x16x32_bf16 v[18:21], v[148:151], v[204:207], v[18:21]
	v_mfma_f32_16x16x32_bf16 v[6:9], v[156:159], v[204:207], v[6:9]
	v_mfma_f32_16x16x32_bf16 v[62:65], v[160:163], v[176:179], v[62:65]
	v_mfma_f32_16x16x32_bf16 v[54:57], v[168:171], v[176:179], v[54:57]
	v_mfma_f32_16x16x32_bf16 v[46:49], v[160:163], v[184:187], v[46:49]
	v_mfma_f32_16x16x32_bf16 v[38:41], v[168:171], v[184:187], v[38:41]
	v_mfma_f32_16x16x32_bf16 v[30:33], v[160:163], v[192:195], v[30:33]
	v_mfma_f32_16x16x32_bf16 v[22:25], v[168:171], v[192:195], v[22:25]
	v_mfma_f32_16x16x32_bf16 v[10:13], v[160:163], v[200:203], v[10:13]
	v_mfma_f32_16x16x32_bf16 v[2:5], v[168:171], v[200:203], v[2:5]
	v_mfma_f32_16x16x32_bf16 v[62:65], v[164:167], v[180:183], v[62:65]
	v_mfma_f32_16x16x32_bf16 v[54:57], v[172:175], v[180:183], v[54:57]
	v_mfma_f32_16x16x32_bf16 v[46:49], v[164:167], v[188:191], v[46:49]
	v_mfma_f32_16x16x32_bf16 v[38:41], v[172:175], v[188:191], v[38:41]
	v_mfma_f32_16x16x32_bf16 v[30:33], v[164:167], v[196:199], v[30:33]
	v_mfma_f32_16x16x32_bf16 v[22:25], v[172:175], v[196:199], v[22:25]
	v_mfma_f32_16x16x32_bf16 v[10:13], v[164:167], v[204:207], v[10:13]
	v_mfma_f32_16x16x32_bf16 v[2:5], v[172:175], v[204:207], v[2:5]
	s_setprio 0
	s_barrier
	s_add_i32 s43, s43, 2
	s_add_u32 s31, s31, 0x100
	s_addc_u32 s41, s41, 0
	s_cmp_gt_u32 s43, 29
	s_mov_b64 s[18:19], s[36:37]
	s_cbranch_scc0 .LBB0_402
	s_and_b64 vcc, exec, s[14:15]
	s_cbranch_vccz .LBB0_405
	s_barrier
